# second timing of the same kernel (O2 gate order, nt LA/BT and UG stores, fused scan pass 1)
# speedup vs baseline: 1.0291x; 1.0025x over previous
; #define PG8_STAGE(bufoff, gbase, voff) do { _Pragma("unroll") for (int _i = 0; _i < 2; ++_i) \
;         __builtin_amdgcn_global_load_lds((const __attribute__((address_space(1))) unsigned*)((const char*)(gbase) + (voff)[_i]), (LAS unsigned*)(lds + (bufoff) + ldsw + _i * 8192), 16, 0, 0); } while (0)
; #define PG8_LDA(dst, b, h) do { _Pragma("unroll") for (int m = 0; m < 4; ++m) _Pragma("unroll") for (int k = 0; k < 2; ++k) dst[m][k] = *(const LAS bf16x8*)(lds + PG8_SA(b, h) + aoff + m * 2048 + k * 1024); } while (0)
; #define PG8_LDB(dst, b, h) do { _Pragma("unroll") for (int n = 0; n < 2; ++n) _Pragma("unroll") for (int k = 0; k < 2; ++k) dst[n][k] = *(const LAS bf16x8*)(lds + PG8_SB(b, h) + boff + n * 2048 + k * 1024); } while (0)
; #define PG8_MMA(ai, bj, At, Bt) do { __builtin_amdgcn_s_setprio(1); _Pragma("unroll") for (int m = 0; m < 4; ++m) _Pragma("unroll") for (int n = 0; n < 2; ++n) _Pragma("unroll") for (int k = 0; k < 2; ++k) \
;         acc[ai][bj][m][n] = __builtin_amdgcn_mfma_f32_16x16x32_bf16(Bt[n][k], At[m][k], acc[ai][bj][m][n], 0, 0, 0); __builtin_amdgcn_s_setprio(0); } while (0)
; #define PG8_WAIT_L(n) asm volatile("s_waitcnt lgkmcnt(" #n ")" ::: "memory")
; template <class Epi>
; __device__ __forceinline__ void gemm_phase(LAS unsigned char* lds, const Gemm g, const StaticOrder& S_in, const Epi& E, int sw) {
;     ...
;         const bool has_next = S.next(ui + 1, nxt);
;         const char* nA = has_next ? PG8_ABASE(nxt) : cA; const char* nB = has_next ? PG8_BBASE(nxt) : cB;
;         for (int t = 0; t < nt; t += 2) {
;             const bool last = (t == nt - 2);
;             const char* a1 = cA + (size_t)(t + 1) * kstep;
;             const char* a2 = last ? nA : cA + (size_t)(t + 2) * kstep; const char* b2 = last ? nB : cB + (size_t)(t + 2) * kstep;
;             const char* a3 = a2 + kstep; const char* b3 = b2 + kstep;
;             PG8_LDB(B0, 0, 0); PG8_SCHED; PG8_LDA(At, 0, 0); PG8_STAGE(PG8_SA(1, 1), a1 + hstepA, voffA);
;             PG8_WAIT_L(8); PG8_BAR; PG8_WAIT_L(0); PG8_MMA(0, 0, At, B0); PG8_BAR; PG8_SCHED;
;             PG8_LDB(B1, 0, 1); PG8_STAGE(PG8_SB(0, 0), b2, voffB);
;             PG8_BAR; PG8_WAIT_L(0); PG8_MMA(0, 1, At, B1); PG8_BAR;
;             PG8_LDA(At, 0, 1); PG8_STAGE(PG8_SA(0, 0), a2, voffA);
;             PG8_BAR; PG8_WAIT_L(0); PG8_MMA(1, 0, At, B0); PG8_BAR; PG8_SCHED;
.Lgate_ord_keep:
.LBB0_428:
	s_ashr_i32 s18, s12, 1
	s_ashr_i32 s17, s16, 31
	s_ashr_i32 s19, s18, 31
	s_lshl_b64 s[18:19], s[18:19], 9
	s_lshl_b64 s[20:21], s[16:17], 20
	s_add_u32 s13, s39, s20
	s_addc_u32 s17, s40, s21
	s_add_u32 s18, s13, s18
	s_addc_u32 s19, s17, s19
	s_and_b64 s[20:21], s[4:5], exec
	s_cselect_b32 s35, s19, s27
	s_cselect_b32 s34, s18, s26
	s_ashr_i32 s13, s12, 31
	s_lshl_b64 s[20:21], s[12:13], 17
	s_add_u32 s20, s41, s20
	s_addc_u32 s21, s42, s21
	s_and_b64 s[30:31], s[4:5], exec
	s_cselect_b32 s31, s21, s29
	s_cselect_b32 s30, s20, s28
	s_add_i32 s17, 0, 0x10000
	v_add_u32_e32 v175, s17, v171
	ds_read_b128 v[18:21], v175
	ds_read_b128 v[22:25], v175 offset:1024
	ds_read_b128 v[26:29], v175 offset:2048
	ds_read_b128 v[30:33], v175 offset:3072
	s_add_u32 s48, s26, 0x80080
	s_addc_u32 s49, s27, 0
	s_add_i32 s50, s23, 0xc000
	v_lshl_add_u64 v[66:67], s[48:49], 0, v[130:131]
	s_mov_b32 m0, s50
	s_add_i32 s13, s23, 0xe000
	ds_read_b128 v[34:37], v174
	ds_read_b128 v[38:41], v174 offset:1024
	ds_read_b128 v[42:45], v174 offset:2048
	ds_read_b128 v[46:49], v174 offset:3072
	ds_read_b128 v[50:53], v174 offset:4096
	ds_read_b128 v[54:57], v174 offset:5120
	ds_read_b128 v[58:61], v174 offset:6144
	ds_read_b128 v[62:65], v174 offset:7168
	global_load_lds_dwordx4 v[66:67], off
	v_lshl_add_u64 v[66:67], s[48:49], 0, v[132:133]
	s_mov_b32 m0, s13
	s_nop 0
	global_load_lds_dwordx4 v[66:67], off
	s_waitcnt lgkmcnt(8)
	s_barrier
	s_waitcnt lgkmcnt(0)
	s_setprio 1
	s_waitcnt lgkmcnt(0)
	v_mfma_f32_16x16x32_bf16 v[66:69], v[18:21], v[34:37], v[10:13]
	v_mfma_f32_16x16x32_bf16 v[70:73], v[26:29], v[34:37], v[14:17]
	v_mfma_f32_16x16x32_bf16 v[74:77], v[18:21], v[42:45], v[10:13]
	v_mfma_f32_16x16x32_bf16 v[78:81], v[26:29], v[42:45], v[14:17]
	v_mfma_f32_16x16x32_bf16 v[82:85], v[18:21], v[50:53], v[10:13]
	v_mfma_f32_16x16x32_bf16 v[86:89], v[26:29], v[50:53], v[14:17]
	v_mfma_f32_16x16x32_bf16 v[90:93], v[18:21], v[58:61], v[10:13]
	v_mfma_f32_16x16x32_bf16 v[94:97], v[26:29], v[58:61], v[14:17]
	v_mfma_f32_16x16x32_bf16 v[66:69], v[22:25], v[38:41], v[66:69]
	v_mfma_f32_16x16x32_bf16 v[70:73], v[30:33], v[38:41], v[70:73]
	v_mfma_f32_16x16x32_bf16 v[74:77], v[22:25], v[46:49], v[74:77]
	v_mfma_f32_16x16x32_bf16 v[78:81], v[30:33], v[46:49], v[78:81]
	v_mfma_f32_16x16x32_bf16 v[82:85], v[22:25], v[54:57], v[82:85]
	v_mfma_f32_16x16x32_bf16 v[86:89], v[30:33], v[54:57], v[86:89]
	v_mfma_f32_16x16x32_bf16 v[90:93], v[22:25], v[62:65], v[90:93]
	v_mfma_f32_16x16x32_bf16 v[94:97], v[30:33], v[62:65], v[94:97]
	s_setprio 0
	s_barrier
	s_add_i32 s51, 0, 0x14000
	v_lshl_add_u64 v[168:169], s[28:29], 0, v[0:1]
	s_mov_b64 s[52:53], 0x100
	s_add_i32 s49, s17, s38
	v_add_u32_e32 v212, s51, v171
	v_lshl_add_u64 v[114:115], v[168:169], 0, s[52:53]
	s_mov_b32 m0, s49
	v_lshl_add_u64 v[172:173], s[28:29], 0, v[134:135]
	s_add_i32 s17, s49, 0x2000
	ds_read_b128 v[98:101], v212
	ds_read_b128 v[102:105], v212 offset:1024
	ds_read_b128 v[106:109], v212 offset:2048
	ds_read_b128 v[110:113], v212 offset:3072
	global_load_lds_dwordx4 v[114:115], off
	v_lshl_add_u64 v[114:115], v[172:173], 0, s[52:53]
	s_mov_b32 m0, s17
	s_nop 0
	global_load_lds_dwordx4 v[114:115], off
	s_barrier
	s_waitcnt lgkmcnt(0)
	s_setprio 1
	s_waitcnt lgkmcnt(0)
	v_mfma_f32_16x16x32_bf16 v[114:117], v[98:101], v[34:37], v[2:5]
	v_mfma_f32_16x16x32_bf16 v[34:37], v[106:109], v[34:37], v[6:9]
	v_mfma_f32_16x16x32_bf16 v[114:117], v[102:105], v[38:41], v[114:117]
	v_mfma_f32_16x16x32_bf16 v[34:37], v[110:113], v[38:41], v[34:37]
	v_mfma_f32_16x16x32_bf16 v[38:41], v[98:101], v[42:45], v[2:5]
	v_mfma_f32_16x16x32_bf16 v[42:45], v[106:109], v[42:45], v[6:9]
	v_mfma_f32_16x16x32_bf16 v[38:41], v[102:105], v[46:49], v[38:41]
	v_mfma_f32_16x16x32_bf16 v[42:45], v[110:113], v[46:49], v[42:45]
	v_mfma_f32_16x16x32_bf16 v[46:49], v[98:101], v[50:53], v[2:5]
	v_mfma_f32_16x16x32_bf16 v[50:53], v[106:109], v[50:53], v[6:9]
	v_mfma_f32_16x16x32_bf16 v[46:49], v[102:105], v[54:57], v[46:49]
	v_mfma_f32_16x16x32_bf16 v[50:53], v[110:113], v[54:57], v[50:53]
	v_mfma_f32_16x16x32_bf16 v[54:57], v[98:101], v[58:61], v[2:5]
	v_mfma_f32_16x16x32_bf16 v[58:61], v[106:109], v[58:61], v[6:9]
	v_mfma_f32_16x16x32_bf16 v[54:57], v[102:105], v[62:65], v[54:57]
	v_mfma_f32_16x16x32_bf16 v[58:61], v[110:113], v[62:65], v[58:61]
	s_setprio 0
	v_lshl_add_u64 v[208:209], s[26:27], 0, v[130:131]
	s_mov_b32 m0, s23
	v_lshl_add_u64 v[152:153], v[208:209], 0, s[52:53]
	v_lshl_add_u64 v[210:211], s[26:27], 0, v[132:133]
	s_barrier
	ds_read_b128 v[62:65], v174 offset:16384
	ds_read_b128 v[118:121], v174 offset:17408
	ds_read_b128 v[122:125], v174 offset:18432
	ds_read_b128 v[126:129], v174 offset:19456
	ds_read_b128 v[136:139], v174 offset:20480
	ds_read_b128 v[140:143], v174 offset:21504
	ds_read_b128 v[144:147], v174 offset:22528
	ds_read_b128 v[148:151], v174 offset:23552
	global_load_lds_dwordx4 v[152:153], off
	v_lshl_add_u64 v[152:153], v[210:211], 0, s[52:53]
	s_mov_b32 m0, s25
	s_nop 0
	global_load_lds_dwordx4 v[152:153], off
	s_barrier
; #define PG8_STAGE(bufoff, gbase, voff) do { _Pragma("unroll") for (int _i = 0; _i < 2; ++_i) \
;         __builtin_amdgcn_global_load_lds((const __attribute__((address_space(1))) unsigned*)((const char*)(gbase) + (voff)[_i]), (LAS unsigned*)(lds + (bufoff) + ldsw + _i * 8192), 16, 0, 0); } while (0)
; #define PG8_LDA(dst, b, h) do { _Pragma("unroll") for (int m = 0; m < 4; ++m) _Pragma("unroll") for (int k = 0; k < 2; ++k) dst[m][k] = *(const LAS bf16x8*)(lds + PG8_SA(b, h) + aoff + m * 2048 + k * 1024); } while (0)
; #define PG8_LDB(dst, b, h) do { _Pragma("unroll") for (int n = 0; n < 2; ++n) _Pragma("unroll") for (int k = 0; k < 2; ++k) dst[n][k] = *(const LAS bf16x8*)(lds + PG8_SB(b, h) + boff + n * 2048 + k * 1024); } while (0)
; #define PG8_MMA(ai, bj, At, Bt) do { __builtin_amdgcn_s_setprio(1); _Pragma("unroll") for (int m = 0; m < 4; ++m) _Pragma("unroll") for (int n = 0; n < 2; ++n) _Pragma("unroll") for (int k = 0; k < 2; ++k) \
;         acc[ai][bj][m][n] = __builtin_amdgcn_mfma_f32_16x16x32_bf16(Bt[n][k], At[m][k], acc[ai][bj][m][n], 0, 0, 0); __builtin_amdgcn_s_setprio(0); } while (0)
; #define PG8_WAIT_V(n) asm volatile("s_waitcnt vmcnt(" #n ")" ::: "memory")
; #define PG8_WAIT_L(n) asm volatile("s_waitcnt lgkmcnt(" #n ")" ::: "memory")
; #define PG8_BAR __builtin_amdgcn_s_barrier()
; #define PG8_SCHED __builtin_amdgcn_sched_barrier(0)
; template <class Epi>
; __device__ __forceinline__ void gemm_phase(LAS unsigned char* lds, const Gemm g, const StaticOrder& S_in, const Epi& E, int sw) {
;     ...
;             PG8_BAR; PG8_WAIT_L(0); PG8_MMA(1, 0, At, B0); PG8_BAR; PG8_SCHED;
;             PG8_STAGE(PG8_SB(0, 1), b2 + hstepB, voffB);
;             PG8_WAIT_V(6); PG8_BAR; PG8_MMA(1, 1, At, B1); PG8_BAR;
;             PG8_LDB(B0, 1, 0); PG8_SCHED; PG8_LDA(At, 1, 0); PG8_STAGE(PG8_SA(0, 1), a2 + hstepA, voffA);
;             PG8_WAIT_L(8); PG8_BAR; PG8_WAIT_L(0); PG8_MMA(0, 0, At, B0); PG8_BAR; PG8_SCHED;
;             PG8_LDB(B1, 1, 1); PG8_STAGE(PG8_SB(1, 0), b3, voffB);
;             PG8_BAR; PG8_WAIT_L(0); PG8_MMA(0, 1, At, B1); PG8_BAR;
	s_waitcnt lgkmcnt(0)
	s_setprio 1
	s_waitcnt lgkmcnt(0)
	v_mfma_f32_16x16x32_bf16 v[152:155], v[18:21], v[62:65], v[10:13]
	v_mfma_f32_16x16x32_bf16 v[156:159], v[26:29], v[62:65], v[14:17]
	v_mfma_f32_16x16x32_bf16 v[160:163], v[18:21], v[122:125], v[10:13]
	v_mfma_f32_16x16x32_bf16 v[164:167], v[26:29], v[122:125], v[14:17]
	v_mfma_f32_16x16x32_bf16 v[176:179], v[18:21], v[136:139], v[10:13]
	v_mfma_f32_16x16x32_bf16 v[180:183], v[26:29], v[136:139], v[14:17]
	v_mfma_f32_16x16x32_bf16 v[10:13], v[18:21], v[144:147], v[10:13]
	v_mfma_f32_16x16x32_bf16 v[14:17], v[26:29], v[144:147], v[14:17]
	v_mfma_f32_16x16x32_bf16 v[152:155], v[22:25], v[118:121], v[152:155]
	v_mfma_f32_16x16x32_bf16 v[156:159], v[30:33], v[118:121], v[156:159]
	v_mfma_f32_16x16x32_bf16 v[160:163], v[22:25], v[126:129], v[160:163]
	v_mfma_f32_16x16x32_bf16 v[164:167], v[30:33], v[126:129], v[164:167]
	v_mfma_f32_16x16x32_bf16 v[10:13], v[22:25], v[148:151], v[10:13]
	v_mfma_f32_16x16x32_bf16 v[14:17], v[30:33], v[148:151], v[14:17]
	v_mfma_f32_16x16x32_bf16 v[176:179], v[22:25], v[140:143], v[176:179]
	v_mfma_f32_16x16x32_bf16 v[180:183], v[30:33], v[140:143], v[180:183]
	s_setprio 0
	s_barrier
	s_add_u32 s52, s28, 0x10100
	s_addc_u32 s53, s29, 0
	s_add_i32 s51, s51, s38
	v_lshl_add_u64 v[18:19], s[52:53], 0, v[0:1]
	s_mov_b32 m0, s51
	s_add_i32 s48, s51, 0x2000
	global_load_lds_dwordx4 v[18:19], off
	v_lshl_add_u64 v[18:19], s[52:53], 0, v[134:135]
	s_mov_b32 m0, s48
	s_nop 0
	global_load_lds_dwordx4 v[18:19], off
	s_waitcnt vmcnt(6)
	s_barrier
	s_setprio 1
	v_mfma_f32_16x16x32_bf16 v[18:21], v[98:101], v[62:65], v[2:5]
	v_mfma_f32_16x16x32_bf16 v[22:25], v[106:109], v[62:65], v[6:9]
	v_mfma_f32_16x16x32_bf16 v[18:21], v[102:105], v[118:121], v[18:21]
	v_mfma_f32_16x16x32_bf16 v[22:25], v[110:113], v[118:121], v[22:25]
	v_mfma_f32_16x16x32_bf16 v[26:29], v[98:101], v[122:125], v[2:5]
	v_mfma_f32_16x16x32_bf16 v[30:33], v[106:109], v[122:125], v[6:9]
	v_mfma_f32_16x16x32_bf16 v[62:65], v[98:101], v[136:139], v[2:5]
	v_mfma_f32_16x16x32_bf16 v[118:121], v[106:109], v[136:139], v[6:9]
	v_mfma_f32_16x16x32_bf16 v[2:5], v[98:101], v[144:147], v[2:5]
	v_mfma_f32_16x16x32_bf16 v[6:9], v[106:109], v[144:147], v[6:9]
	v_mfma_f32_16x16x32_bf16 v[26:29], v[102:105], v[126:129], v[26:29]
	v_mfma_f32_16x16x32_bf16 v[30:33], v[110:113], v[126:129], v[30:33]
	v_mfma_f32_16x16x32_bf16 v[62:65], v[102:105], v[140:143], v[62:65]
	v_mfma_f32_16x16x32_bf16 v[118:121], v[110:113], v[140:143], v[118:121]
	v_mfma_f32_16x16x32_bf16 v[2:5], v[102:105], v[148:151], v[2:5]
	v_mfma_f32_16x16x32_bf16 v[6:9], v[110:113], v[148:151], v[6:9]
	s_setprio 0
	s_add_i32 s54, 0, 0x18000
	v_add_u32_e32 v220, s54, v171
	s_barrier
	ds_read_b128 v[98:101], v220
	ds_read_b128 v[102:105], v220 offset:1024
	ds_read_b128 v[106:109], v220 offset:2048
	ds_read_b128 v[110:113], v220 offset:3072
	s_add_u32 s52, s26, 0x80100
	s_addc_u32 s53, s27, 0
	s_mov_b32 m0, s43
	v_lshl_add_u64 v[192:193], s[52:53], 0, v[130:131]
	ds_read_b128 v[122:125], v174 offset:32768
	ds_read_b128 v[126:129], v174 offset:33792
	ds_read_b128 v[136:139], v174 offset:34816
	ds_read_b128 v[140:143], v174 offset:35840
	ds_read_b128 v[144:147], v174 offset:36864
	ds_read_b128 v[148:151], v174 offset:37888
	ds_read_b128 v[184:187], v174 offset:38912
	ds_read_b128 v[188:191], v174 offset:39936
	global_load_lds_dwordx4 v[192:193], off
	v_lshl_add_u64 v[192:193], s[52:53], 0, v[132:133]
	s_mov_b32 m0, s44
	s_nop 0
	global_load_lds_dwordx4 v[192:193], off
	s_waitcnt lgkmcnt(8)
	s_barrier
	s_waitcnt lgkmcnt(0)
	s_setprio 1
	s_waitcnt lgkmcnt(0)
	v_mfma_f32_16x16x32_bf16 v[66:69], v[98:101], v[122:125], v[66:69]
	v_mfma_f32_16x16x32_bf16 v[70:73], v[106:109], v[122:125], v[70:73]
	v_mfma_f32_16x16x32_bf16 v[74:77], v[98:101], v[136:139], v[74:77]
	v_mfma_f32_16x16x32_bf16 v[78:81], v[106:109], v[136:139], v[78:81]
	v_mfma_f32_16x16x32_bf16 v[82:85], v[98:101], v[144:147], v[82:85]
	v_mfma_f32_16x16x32_bf16 v[86:89], v[106:109], v[144:147], v[86:89]
	v_mfma_f32_16x16x32_bf16 v[90:93], v[98:101], v[184:187], v[90:93]
	v_mfma_f32_16x16x32_bf16 v[94:97], v[106:109], v[184:187], v[94:97]
	v_mfma_f32_16x16x32_bf16 v[66:69], v[102:105], v[126:129], v[66:69]
	v_mfma_f32_16x16x32_bf16 v[70:73], v[110:113], v[126:129], v[70:73]
	v_mfma_f32_16x16x32_bf16 v[74:77], v[102:105], v[140:143], v[74:77]
	v_mfma_f32_16x16x32_bf16 v[78:81], v[110:113], v[140:143], v[78:81]
	v_mfma_f32_16x16x32_bf16 v[82:85], v[102:105], v[148:151], v[82:85]
	v_mfma_f32_16x16x32_bf16 v[86:89], v[110:113], v[148:151], v[86:89]
	v_mfma_f32_16x16x32_bf16 v[90:93], v[102:105], v[188:191], v[90:93]
	v_mfma_f32_16x16x32_bf16 v[94:97], v[110:113], v[188:191], v[94:97]
	s_setprio 0
	s_barrier
	s_add_i32 s56, 0, 0x1c000
	s_mov_b64 s[58:59], 0x180
	s_add_i32 s53, s54, s38
	v_add_u32_e32 v232, s56, v171
	v_lshl_add_u64 v[168:169], v[168:169], 0, s[58:59]
	s_mov_b32 m0, s53
	s_add_i32 s52, s53, 0x2000
	ds_read_b128 v[192:195], v232
	ds_read_b128 v[196:199], v232 offset:1024
	ds_read_b128 v[200:203], v232 offset:2048
	ds_read_b128 v[204:207], v232 offset:3072
	global_load_lds_dwordx4 v[168:169], off
	v_lshl_add_u64 v[168:169], v[172:173], 0, s[58:59]
	s_mov_b32 m0, s52
	s_nop 0
	global_load_lds_dwordx4 v[168:169], off
	s_barrier
; #define PG8_STAGE(bufoff, gbase, voff) do { _Pragma("unroll") for (int _i = 0; _i < 2; ++_i) \
;         __builtin_amdgcn_global_load_lds((const __attribute__((address_space(1))) unsigned*)((const char*)(gbase) + (voff)[_i]), (LAS unsigned*)(lds + (bufoff) + ldsw + _i * 8192), 16, 0, 0); } while (0)
; #define PG8_LDA(dst, b, h) do { _Pragma("unroll") for (int m = 0; m < 4; ++m) _Pragma("unroll") for (int k = 0; k < 2; ++k) dst[m][k] = *(const LAS bf16x8*)(lds + PG8_SA(b, h) + aoff + m * 2048 + k * 1024); } while (0)
; #define PG8_LDB(dst, b, h) do { _Pragma("unroll") for (int n = 0; n < 2; ++n) _Pragma("unroll") for (int k = 0; k < 2; ++k) dst[n][k] = *(const LAS bf16x8*)(lds + PG8_SB(b, h) + boff + n * 2048 + k * 1024); } while (0)
; #define PG8_WAIT_V(n) asm volatile("s_waitcnt vmcnt(" #n ")" ::: "memory")
; #define PG8_WAIT_L(n) asm volatile("s_waitcnt lgkmcnt(" #n ")" ::: "memory")
; #define PG8_BAR __builtin_amdgcn_s_barrier()
; template <class Epi>
; __device__ __forceinline__ void gemm_phase(LAS unsigned char* lds, const Gemm g, const StaticOrder& S_in, const Epi& E, int sw) {
;     ...
;             PG8_LDB(B0, 0, 0); PG8_SCHED; PG8_LDA(At, 0, 0); PG8_STAGE(PG8_SA(1, 1), a1 + hstepA, voffA);
;             PG8_WAIT_L(8); PG8_BAR; PG8_WAIT_L(0); PG8_MMA(0, 0, At, B0); PG8_BAR; PG8_SCHED;
;             PG8_LDB(B1, 0, 1); PG8_STAGE(PG8_SB(0, 0), b2, voffB);
;             PG8_BAR; PG8_WAIT_L(0); PG8_MMA(0, 1, At, B1); PG8_BAR;
;             PG8_LDA(At, 0, 1); PG8_STAGE(PG8_SA(0, 0), a2, voffA);
;             PG8_BAR; PG8_WAIT_L(0); PG8_MMA(1, 0, At, B0); PG8_BAR; PG8_SCHED;
;             PG8_STAGE(PG8_SB(0, 1), b2 + hstepB, voffB);
;             PG8_WAIT_V(6); PG8_BAR; PG8_MMA(1, 1, At, B1); PG8_BAR;
;             PG8_LDB(B0, 1, 0); PG8_SCHED; PG8_LDA(At, 1, 0); PG8_STAGE(PG8_SA(0, 1), a2 + hstepA, voffA);
;             PG8_WAIT_L(8); PG8_BAR; PG8_WAIT_L(0); PG8_MMA(0, 0, At, B0); PG8_BAR; PG8_SCHED;
;             PG8_LDB(B1, 1, 1); PG8_STAGE(PG8_SB(1, 0), b3, voffB);
;             PG8_BAR; PG8_WAIT_L(0); PG8_MMA(0, 1, At, B1); PG8_BAR;
;             PG8_LDA(At, 1, 1); PG8_STAGE(PG8_SA(1, 0), a3, voffA);
;             PG8_BAR; PG8_WAIT_L(0); PG8_MMA(1, 0, At, B0); PG8_BAR; PG8_SCHED;
;             PG8_STAGE(PG8_SB(1, 1), b3 + hstepB, voffB);
;             PG8_WAIT_V(6); PG8_BAR; PG8_MMA(1, 1, At, B1); PG8_BAR;
	s_waitcnt lgkmcnt(0)
	s_setprio 1
	s_waitcnt lgkmcnt(0)
	v_mfma_f32_16x16x32_bf16 v[114:117], v[192:195], v[122:125], v[114:117]
	v_mfma_f32_16x16x32_bf16 v[34:37], v[200:203], v[122:125], v[34:37]
	v_mfma_f32_16x16x32_bf16 v[38:41], v[192:195], v[136:139], v[38:41]
	v_mfma_f32_16x16x32_bf16 v[42:45], v[200:203], v[136:139], v[42:45]
	v_mfma_f32_16x16x32_bf16 v[46:49], v[192:195], v[144:147], v[46:49]
	v_mfma_f32_16x16x32_bf16 v[50:53], v[200:203], v[144:147], v[50:53]
	v_mfma_f32_16x16x32_bf16 v[54:57], v[192:195], v[184:187], v[54:57]
	v_mfma_f32_16x16x32_bf16 v[58:61], v[200:203], v[184:187], v[58:61]
	v_mfma_f32_16x16x32_bf16 v[114:117], v[196:199], v[126:129], v[114:117]
	v_mfma_f32_16x16x32_bf16 v[34:37], v[204:207], v[126:129], v[34:37]
	v_mfma_f32_16x16x32_bf16 v[38:41], v[196:199], v[140:143], v[38:41]
	v_mfma_f32_16x16x32_bf16 v[42:45], v[204:207], v[140:143], v[42:45]
	v_mfma_f32_16x16x32_bf16 v[46:49], v[196:199], v[148:151], v[46:49]
	v_mfma_f32_16x16x32_bf16 v[50:53], v[204:207], v[148:151], v[50:53]
	v_mfma_f32_16x16x32_bf16 v[54:57], v[196:199], v[188:191], v[54:57]
	v_mfma_f32_16x16x32_bf16 v[58:61], v[204:207], v[188:191], v[58:61]
	s_setprio 0
	s_mov_b32 m0, s45
	v_lshl_add_u64 v[168:169], v[208:209], 0, s[58:59]
	s_barrier
	ds_read_b128 v[122:125], v174 offset:49152
	ds_read_b128 v[126:129], v174 offset:50176
	ds_read_b128 v[136:139], v174 offset:51200
	ds_read_b128 v[140:143], v174 offset:52224
	ds_read_b128 v[144:147], v174 offset:53248
	ds_read_b128 v[148:151], v174 offset:54272
	ds_read_b128 v[184:187], v174 offset:55296
	ds_read_b128 v[188:191], v174 offset:56320
	global_load_lds_dwordx4 v[168:169], off
	v_lshl_add_u64 v[168:169], v[210:211], 0, s[58:59]
	s_mov_b32 m0, s46
	s_nop 0
	global_load_lds_dwordx4 v[168:169], off
	s_barrier
	s_waitcnt lgkmcnt(0)
	s_setprio 1
	s_waitcnt lgkmcnt(0)
	v_mfma_f32_16x16x32_bf16 v[152:155], v[98:101], v[122:125], v[152:155]
	v_mfma_f32_16x16x32_bf16 v[156:159], v[106:109], v[122:125], v[156:159]
	v_mfma_f32_16x16x32_bf16 v[160:163], v[98:101], v[136:139], v[160:163]
	v_mfma_f32_16x16x32_bf16 v[164:167], v[106:109], v[136:139], v[164:167]
	v_mfma_f32_16x16x32_bf16 v[10:13], v[98:101], v[184:187], v[10:13]
	v_mfma_f32_16x16x32_bf16 v[14:17], v[106:109], v[184:187], v[14:17]
	v_mfma_f32_16x16x32_bf16 v[152:155], v[102:105], v[126:129], v[152:155]
	v_mfma_f32_16x16x32_bf16 v[156:159], v[110:113], v[126:129], v[156:159]
	v_mfma_f32_16x16x32_bf16 v[160:163], v[102:105], v[140:143], v[160:163]
	v_mfma_f32_16x16x32_bf16 v[164:167], v[110:113], v[140:143], v[164:167]
	v_mfma_f32_16x16x32_bf16 v[176:179], v[98:101], v[144:147], v[176:179]
	v_mfma_f32_16x16x32_bf16 v[180:183], v[106:109], v[144:147], v[180:183]
	v_mfma_f32_16x16x32_bf16 v[10:13], v[102:105], v[188:191], v[10:13]
	v_mfma_f32_16x16x32_bf16 v[14:17], v[110:113], v[188:191], v[14:17]
	v_mfma_f32_16x16x32_bf16 v[176:179], v[102:105], v[148:151], v[176:179]
	v_mfma_f32_16x16x32_bf16 v[180:183], v[110:113], v[148:151], v[180:183]
	s_setprio 0
	s_barrier
	s_add_u32 s54, s28, 0x10180
	s_addc_u32 s55, s29, 0
	s_add_i32 s29, s56, s38
	v_lshl_add_u64 v[98:99], s[54:55], 0, v[0:1]
	s_mov_b32 m0, s29
	s_add_i32 s28, s29, 0x2000
	global_load_lds_dwordx4 v[98:99], off
	v_lshl_add_u64 v[98:99], s[54:55], 0, v[134:135]
	s_mov_b32 m0, s28
	s_nop 0
	global_load_lds_dwordx4 v[98:99], off
	s_waitcnt vmcnt(6)
	s_barrier
	s_setprio 1
	v_mfma_f32_16x16x32_bf16 v[18:21], v[192:195], v[122:125], v[18:21]
	v_mfma_f32_16x16x32_bf16 v[22:25], v[200:203], v[122:125], v[22:25]
	v_mfma_f32_16x16x32_bf16 v[26:29], v[192:195], v[136:139], v[26:29]
	v_mfma_f32_16x16x32_bf16 v[30:33], v[200:203], v[136:139], v[30:33]
	v_mfma_f32_16x16x32_bf16 v[62:65], v[192:195], v[144:147], v[62:65]
	v_mfma_f32_16x16x32_bf16 v[98:101], v[200:203], v[144:147], v[118:121]
	v_mfma_f32_16x16x32_bf16 v[2:5], v[192:195], v[184:187], v[2:5]
	v_mfma_f32_16x16x32_bf16 v[6:9], v[200:203], v[184:187], v[6:9]
	v_mfma_f32_16x16x32_bf16 v[18:21], v[196:199], v[126:129], v[18:21]
	v_mfma_f32_16x16x32_bf16 v[22:25], v[204:207], v[126:129], v[22:25]
	v_mfma_f32_16x16x32_bf16 v[26:29], v[196:199], v[140:143], v[26:29]
	v_mfma_f32_16x16x32_bf16 v[30:33], v[204:207], v[140:143], v[30:33]
	v_mfma_f32_16x16x32_bf16 v[62:65], v[196:199], v[148:151], v[62:65]
	v_mfma_f32_16x16x32_bf16 v[98:101], v[204:207], v[148:151], v[98:101]
	v_mfma_f32_16x16x32_bf16 v[2:5], v[196:199], v[188:191], v[2:5]
	v_mfma_f32_16x16x32_bf16 v[6:9], v[204:207], v[188:191], v[6:9]
	s_setprio 0
	s_barrier
	ds_read_b128 v[102:105], v175
	ds_read_b128 v[106:109], v175 offset:1024
	ds_read_b128 v[110:113], v175 offset:2048
	ds_read_b128 v[118:121], v175 offset:3072
	s_add_u32 s26, s26, 0x80180
	s_addc_u32 s27, s27, 0
	s_mov_b32 m0, s50
	v_lshl_add_u64 v[168:169], s[26:27], 0, v[130:131]
	ds_read_b128 v[122:125], v174
	ds_read_b128 v[126:129], v174 offset:1024
	ds_read_b128 v[136:139], v174 offset:2048
	ds_read_b128 v[140:143], v174 offset:3072
	ds_read_b128 v[144:147], v174 offset:4096
	ds_read_b128 v[148:151], v174 offset:5120
	ds_read_b128 v[184:187], v174 offset:6144
	ds_read_b128 v[188:191], v174 offset:7168
	global_load_lds_dwordx4 v[168:169], off
	v_lshl_add_u64 v[168:169], s[26:27], 0, v[132:133]
	s_mov_b32 m0, s13
	s_nop 0
	global_load_lds_dwordx4 v[168:169], off
	s_waitcnt lgkmcnt(8)
	s_barrier
; #define PG8_STAGE(bufoff, gbase, voff) do { _Pragma("unroll") for (int _i = 0; _i < 2; ++_i) \
;         __builtin_amdgcn_global_load_lds((const __attribute__((address_space(1))) unsigned*)((const char*)(gbase) + (voff)[_i]), (LAS unsigned*)(lds + (bufoff) + ldsw + _i * 8192), 16, 0, 0); } while (0)
; #define PG8_LDA(dst, b, h) do { _Pragma("unroll") for (int m = 0; m < 4; ++m) _Pragma("unroll") for (int k = 0; k < 2; ++k) dst[m][k] = *(const LAS bf16x8*)(lds + PG8_SA(b, h) + aoff + m * 2048 + k * 1024); } while (0)
; #define PG8_LDB(dst, b, h) do { _Pragma("unroll") for (int n = 0; n < 2; ++n) _Pragma("unroll") for (int k = 0; k < 2; ++k) dst[n][k] = *(const LAS bf16x8*)(lds + PG8_SB(b, h) + boff + n * 2048 + k * 1024); } while (0)
; #define PG8_BAR __builtin_amdgcn_s_barrier()
; template <class Epi>
; __device__ __forceinline__ void gemm_phase(LAS unsigned char* lds, const Gemm g, const StaticOrder& S_in, const Epi& E, int sw) {
;     ...
;             const char* a2 = last ? nA : cA + (size_t)(t + 2) * kstep; const char* b2 = last ? nB : cB + (size_t)(t + 2) * kstep;
;             const char* a3 = a2 + kstep; const char* b3 = b2 + kstep;
;             PG8_LDB(B0, 0, 0); PG8_SCHED; PG8_LDA(At, 0, 0); PG8_STAGE(PG8_SA(1, 1), a1 + hstepA, voffA);
;             PG8_WAIT_L(8); PG8_BAR; PG8_WAIT_L(0); PG8_MMA(0, 0, At, B0); PG8_BAR; PG8_SCHED;
;             PG8_LDB(B1, 0, 1); PG8_STAGE(PG8_SB(0, 0), b2, voffB);
;             PG8_BAR; PG8_WAIT_L(0); PG8_MMA(0, 1, At, B1); PG8_BAR;
;             PG8_LDA(At, 0, 1); PG8_STAGE(PG8_SA(0, 0), a2, voffA);
;             PG8_BAR; PG8_WAIT_L(0); PG8_MMA(1, 0, At, B0); PG8_BAR; PG8_SCHED;
;             PG8_STAGE(PG8_SB(0, 1), b2 + hstepB, voffB);
;             PG8_WAIT_V(6); PG8_BAR; PG8_MMA(1, 1, At, B1); PG8_BAR;
;             PG8_LDB(B0, 1, 0); PG8_SCHED; PG8_LDA(At, 1, 0); PG8_STAGE(PG8_SA(0, 1), a2 + hstepA, voffA);
;             PG8_WAIT_L(8); PG8_BAR; PG8_WAIT_L(0); PG8_MMA(0, 0, At, B0); PG8_BAR; PG8_SCHED;
;             PG8_LDB(B1, 1, 1); PG8_STAGE(PG8_SB(1, 0), b3, voffB);
;             PG8_BAR; PG8_WAIT_L(0); PG8_MMA(0, 1, At, B1); PG8_BAR;
;             PG8_LDA(At, 1, 1); PG8_STAGE(PG8_SA(1, 0), a3, voffA);
;             PG8_BAR; PG8_WAIT_L(0); PG8_MMA(1, 0, At, B0); PG8_BAR; PG8_SCHED;
;             PG8_STAGE(PG8_SB(1, 1), b3 + hstepB, voffB);
;             PG8_WAIT_V(6); PG8_BAR; PG8_MMA(1, 1, At, B1); PG8_BAR;
	s_waitcnt lgkmcnt(0)
	s_setprio 1
	s_waitcnt lgkmcnt(0)
	v_mfma_f32_16x16x32_bf16 v[66:69], v[102:105], v[122:125], v[66:69]
	v_mfma_f32_16x16x32_bf16 v[70:73], v[110:113], v[122:125], v[70:73]
	v_mfma_f32_16x16x32_bf16 v[74:77], v[102:105], v[136:139], v[74:77]
	v_mfma_f32_16x16x32_bf16 v[78:81], v[110:113], v[136:139], v[78:81]
	v_mfma_f32_16x16x32_bf16 v[82:85], v[102:105], v[144:147], v[82:85]
	v_mfma_f32_16x16x32_bf16 v[86:89], v[110:113], v[144:147], v[86:89]
	v_mfma_f32_16x16x32_bf16 v[90:93], v[102:105], v[184:187], v[90:93]
	v_mfma_f32_16x16x32_bf16 v[94:97], v[110:113], v[184:187], v[94:97]
	v_mfma_f32_16x16x32_bf16 v[66:69], v[106:109], v[126:129], v[66:69]
	v_mfma_f32_16x16x32_bf16 v[70:73], v[118:121], v[126:129], v[70:73]
	v_mfma_f32_16x16x32_bf16 v[74:77], v[106:109], v[140:143], v[74:77]
	v_mfma_f32_16x16x32_bf16 v[78:81], v[118:121], v[140:143], v[78:81]
	v_mfma_f32_16x16x32_bf16 v[82:85], v[106:109], v[148:151], v[82:85]
	v_mfma_f32_16x16x32_bf16 v[86:89], v[118:121], v[148:151], v[86:89]
	v_mfma_f32_16x16x32_bf16 v[90:93], v[106:109], v[188:191], v[90:93]
	v_mfma_f32_16x16x32_bf16 v[94:97], v[118:121], v[188:191], v[94:97]
	s_setprio 0
	s_barrier
	s_mov_b32 m0, s49
	v_lshl_add_u64 v[168:169], s[30:31], 0, v[0:1]
	ds_read_b128 v[192:195], v212
	ds_read_b128 v[196:199], v212 offset:1024
	ds_read_b128 v[200:203], v212 offset:2048
	ds_read_b128 v[204:207], v212 offset:3072
	global_load_lds_dwordx4 v[168:169], off
	v_lshl_add_u64 v[172:173], s[30:31], 0, v[134:135]
	s_mov_b32 m0, s17
	s_nop 0
	global_load_lds_dwordx4 v[172:173], off
	s_barrier
	s_waitcnt lgkmcnt(0)
	s_setprio 1
	s_waitcnt lgkmcnt(0)
	v_mfma_f32_16x16x32_bf16 v[50:53], v[200:203], v[144:147], v[50:53]
	v_mfma_f32_16x16x32_bf16 v[38:41], v[192:195], v[136:139], v[38:41]
	v_mfma_f32_16x16x32_bf16 v[42:45], v[200:203], v[136:139], v[42:45]
	v_mfma_f32_16x16x32_bf16 v[136:139], v[204:207], v[148:151], v[50:53]
	v_mfma_f32_16x16x32_bf16 v[50:53], v[192:195], v[184:187], v[54:57]
	v_mfma_f32_16x16x32_bf16 v[34:37], v[200:203], v[122:125], v[34:37]
	v_mfma_f32_16x16x32_bf16 v[38:41], v[196:199], v[140:143], v[38:41]
	v_mfma_f32_16x16x32_bf16 v[42:45], v[204:207], v[140:143], v[42:45]
	v_mfma_f32_16x16x32_bf16 v[46:49], v[192:195], v[144:147], v[46:49]
	v_mfma_f32_16x16x32_bf16 v[140:143], v[196:199], v[188:191], v[50:53]
	v_mfma_f32_16x16x32_bf16 v[50:53], v[200:203], v[184:187], v[58:61]
	v_mfma_f32_16x16x32_bf16 v[114:117], v[192:195], v[122:125], v[114:117]
	v_mfma_f32_16x16x32_bf16 v[34:37], v[204:207], v[126:129], v[34:37]
	v_mfma_f32_16x16x32_bf16 v[46:49], v[196:199], v[148:151], v[46:49]
	v_mfma_f32_16x16x32_bf16 v[144:147], v[204:207], v[188:191], v[50:53]
	v_mfma_f32_16x16x32_bf16 v[208:211], v[196:199], v[126:129], v[114:117]
	s_setprio 0
	s_mov_b32 m0, s23
	v_lshl_add_u64 v[240:241], s[34:35], 0, v[130:131]
	s_barrier
	ds_read_b128 v[50:53], v174 offset:16384
	ds_read_b128 v[54:57], v174 offset:17408
	ds_read_b128 v[58:61], v174 offset:18432
	ds_read_b128 v[114:117], v174 offset:19456
	ds_read_b128 v[122:125], v174 offset:20480
	ds_read_b128 v[126:129], v174 offset:21504
	ds_read_b128 v[148:151], v174 offset:22528
	ds_read_b128 v[184:187], v174 offset:23552
	global_load_lds_dwordx4 v[240:241], off
	v_lshl_add_u64 v[242:243], s[34:35], 0, v[132:133]
	s_mov_b32 m0, s25
	s_nop 0
	global_load_lds_dwordx4 v[242:243], off
	s_barrier
	s_waitcnt lgkmcnt(0)
	s_setprio 1
	s_waitcnt lgkmcnt(0)
	v_mfma_f32_16x16x32_bf16 v[152:155], v[102:105], v[50:53], v[152:155]
	v_mfma_f32_16x16x32_bf16 v[156:159], v[110:113], v[50:53], v[156:159]
	v_mfma_f32_16x16x32_bf16 v[160:163], v[102:105], v[58:61], v[160:163]
	v_mfma_f32_16x16x32_bf16 v[164:167], v[110:113], v[58:61], v[164:167]
	v_mfma_f32_16x16x32_bf16 v[10:13], v[102:105], v[148:151], v[10:13]
	v_mfma_f32_16x16x32_bf16 v[14:17], v[110:113], v[148:151], v[14:17]
	v_mfma_f32_16x16x32_bf16 v[152:155], v[106:109], v[54:57], v[152:155]
	v_mfma_f32_16x16x32_bf16 v[156:159], v[118:121], v[54:57], v[156:159]
	v_mfma_f32_16x16x32_bf16 v[160:163], v[106:109], v[114:117], v[160:163]
	v_mfma_f32_16x16x32_bf16 v[164:167], v[118:121], v[114:117], v[164:167]
	v_mfma_f32_16x16x32_bf16 v[176:179], v[102:105], v[122:125], v[176:179]
	v_mfma_f32_16x16x32_bf16 v[180:183], v[110:113], v[122:125], v[180:183]
	v_mfma_f32_16x16x32_bf16 v[10:13], v[106:109], v[184:187], v[10:13]
	v_mfma_f32_16x16x32_bf16 v[14:17], v[118:121], v[184:187], v[14:17]
	v_mfma_f32_16x16x32_bf16 v[176:179], v[106:109], v[126:129], v[176:179]
	v_mfma_f32_16x16x32_bf16 v[180:183], v[118:121], v[126:129], v[180:183]
	s_setprio 0
	s_barrier
	s_add_u32 s26, s30, 0x10000
	s_addc_u32 s27, s31, 0
	s_mov_b32 m0, s51
	v_lshl_add_u64 v[102:103], s[26:27], 0, v[0:1]
	global_load_lds_dwordx4 v[102:103], off
	v_lshl_add_u64 v[102:103], s[26:27], 0, v[134:135]
	s_mov_b32 m0, s48
	s_nop 0
	global_load_lds_dwordx4 v[102:103], off
	s_waitcnt vmcnt(6)
	s_barrier
	s_setprio 1
	v_mfma_f32_16x16x32_bf16 v[26:29], v[192:195], v[58:61], v[26:29]
	v_mfma_f32_16x16x32_bf16 v[188:191], v[196:199], v[114:117], v[26:29]
	v_mfma_f32_16x16x32_bf16 v[26:29], v[200:203], v[58:61], v[30:33]
	v_mfma_f32_16x16x32_bf16 v[18:21], v[192:195], v[50:53], v[18:21]
	v_mfma_f32_16x16x32_bf16 v[22:25], v[200:203], v[50:53], v[22:25]
	v_mfma_f32_16x16x32_bf16 v[212:215], v[204:207], v[114:117], v[26:29]
	v_mfma_f32_16x16x32_bf16 v[26:29], v[192:195], v[122:125], v[62:65]
	v_mfma_f32_16x16x32_bf16 v[2:5], v[192:195], v[148:151], v[2:5]
	v_mfma_f32_16x16x32_bf16 v[6:9], v[200:203], v[148:151], v[6:9]
	v_mfma_f32_16x16x32_bf16 v[18:21], v[196:199], v[54:57], v[18:21]
	v_mfma_f32_16x16x32_bf16 v[22:25], v[204:207], v[54:57], v[22:25]
	v_mfma_f32_16x16x32_bf16 v[62:65], v[196:199], v[126:129], v[26:29]
	v_mfma_f32_16x16x32_bf16 v[26:29], v[200:203], v[122:125], v[98:101]
	v_mfma_f32_16x16x32_bf16 v[2:5], v[196:199], v[184:187], v[2:5]
	v_mfma_f32_16x16x32_bf16 v[6:9], v[204:207], v[184:187], v[6:9]
	v_mfma_f32_16x16x32_bf16 v[216:219], v[204:207], v[126:129], v[26:29]
	s_setprio 0
	s_barrier
; #define PG8_STAGE(bufoff, gbase, voff) do { _Pragma("unroll") for (int _i = 0; _i < 2; ++_i) \
;         __builtin_amdgcn_global_load_lds((const __attribute__((address_space(1))) unsigned*)((const char*)(gbase) + (voff)[_i]), (LAS unsigned*)(lds + (bufoff) + ldsw + _i * 8192), 16, 0, 0); } while (0)
; #define PG8_LDA(dst, b, h) do { _Pragma("unroll") for (int m = 0; m < 4; ++m) _Pragma("unroll") for (int k = 0; k < 2; ++k) dst[m][k] = *(const LAS bf16x8*)(lds + PG8_SA(b, h) + aoff + m * 2048 + k * 1024); } while (0)
; #define PG8_LDB(dst, b, h) do { _Pragma("unroll") for (int n = 0; n < 2; ++n) _Pragma("unroll") for (int k = 0; k < 2; ++k) dst[n][k] = *(const LAS bf16x8*)(lds + PG8_SB(b, h) + boff + n * 2048 + k * 1024); } while (0)
; #define PG8_MMA(ai, bj, At, Bt) do { __builtin_amdgcn_s_setprio(1); _Pragma("unroll") for (int m = 0; m < 4; ++m) _Pragma("unroll") for (int n = 0; n < 2; ++n) _Pragma("unroll") for (int k = 0; k < 2; ++k) \
;         acc[ai][bj][m][n] = __builtin_amdgcn_mfma_f32_16x16x32_bf16(Bt[n][k], At[m][k], acc[ai][bj][m][n], 0, 0, 0); __builtin_amdgcn_s_setprio(0); } while (0)
; #define PG8_WAIT_V(n) asm volatile("s_waitcnt vmcnt(" #n ")" ::: "memory")
; #define PG8_WAIT_L(n) asm volatile("s_waitcnt lgkmcnt(" #n ")" ::: "memory")
; #define PG8_BAR __builtin_amdgcn_s_barrier()
; template <class Epi>
; __device__ __forceinline__ void gemm_phase(LAS unsigned char* lds, const Gemm g, const StaticOrder& S_in, const Epi& E, int sw) {
;     ...
;             PG8_LDA(At, 0, 1); PG8_STAGE(PG8_SA(0, 0), a2, voffA);
;             PG8_BAR; PG8_WAIT_L(0); PG8_MMA(1, 0, At, B0); PG8_BAR; PG8_SCHED;
;             PG8_STAGE(PG8_SB(0, 1), b2 + hstepB, voffB);
;             PG8_WAIT_V(6); PG8_BAR; PG8_MMA(1, 1, At, B1); PG8_BAR;
;             PG8_LDB(B0, 1, 0); PG8_SCHED; PG8_LDA(At, 1, 0); PG8_STAGE(PG8_SA(0, 1), a2 + hstepA, voffA);
;             PG8_WAIT_L(8); PG8_BAR; PG8_WAIT_L(0); PG8_MMA(0, 0, At, B0); PG8_BAR; PG8_SCHED;
;             PG8_LDB(B1, 1, 1); PG8_STAGE(PG8_SB(1, 0), b3, voffB);
;             PG8_BAR; PG8_WAIT_L(0); PG8_MMA(0, 1, At, B1); PG8_BAR;
;             PG8_LDA(At, 1, 1); PG8_STAGE(PG8_SA(1, 0), a3, voffA);
;             PG8_BAR; PG8_WAIT_L(0); PG8_MMA(1, 0, At, B0); PG8_BAR; PG8_SCHED;
;             PG8_STAGE(PG8_SB(1, 1), b3 + hstepB, voffB);
;             PG8_WAIT_V(6); PG8_BAR; PG8_MMA(1, 1, At, B1); PG8_BAR;
	s_nop 2
	ds_read_b128 v[26:29], v220
	ds_read_b128 v[30:33], v220 offset:1024
	ds_read_b128 v[148:151], v220 offset:2048
	ds_read_b128 v[184:187], v220 offset:3072
	s_add_u32 s26, s34, 0x80000
	s_addc_u32 s27, s35, 0
	s_mov_b32 m0, s43
	v_lshl_add_u64 v[58:59], s[26:27], 0, v[130:131]
	ds_read_b128 v[50:53], v174 offset:32768
	ds_read_b128 v[54:57], v174 offset:33792
	ds_read_b128 v[98:101], v174 offset:34816
	ds_read_b128 v[102:105], v174 offset:35840
	ds_read_b128 v[110:113], v174 offset:36864
	ds_read_b128 v[192:195], v174 offset:37888
	ds_read_b128 v[196:199], v174 offset:38912
	ds_read_b128 v[200:203], v174 offset:39936
	global_load_lds_dwordx4 v[58:59], off
	v_lshl_add_u64 v[58:59], s[26:27], 0, v[132:133]
	s_mov_b32 m0, s44
	s_nop 0
	global_load_lds_dwordx4 v[58:59], off
	s_waitcnt lgkmcnt(8)
	s_barrier
	s_waitcnt lgkmcnt(0)
	s_setprio 1
	s_waitcnt lgkmcnt(0)
	v_mfma_f32_16x16x32_bf16 v[58:61], v[26:29], v[50:53], v[66:69]
	v_mfma_f32_16x16x32_bf16 v[204:207], v[30:33], v[54:57], v[58:61]
	v_mfma_f32_16x16x32_bf16 v[58:61], v[148:151], v[50:53], v[70:73]
	v_mfma_f32_16x16x32_bf16 v[220:223], v[184:187], v[54:57], v[58:61]
	v_mfma_f32_16x16x32_bf16 v[58:61], v[26:29], v[98:101], v[74:77]
	v_mfma_f32_16x16x32_bf16 v[224:227], v[30:33], v[102:105], v[58:61]
	v_mfma_f32_16x16x32_bf16 v[58:61], v[148:151], v[98:101], v[78:81]
	v_mfma_f32_16x16x32_bf16 v[126:129], v[184:187], v[102:105], v[58:61]
	v_mfma_f32_16x16x32_bf16 v[58:61], v[26:29], v[110:113], v[82:85]
	v_mfma_f32_16x16x32_bf16 v[122:125], v[30:33], v[192:195], v[58:61]
	v_mfma_f32_16x16x32_bf16 v[58:61], v[148:151], v[110:113], v[86:89]
	v_mfma_f32_16x16x32_bf16 v[118:121], v[184:187], v[192:195], v[58:61]
	v_mfma_f32_16x16x32_bf16 v[58:61], v[26:29], v[196:199], v[90:93]
	v_mfma_f32_16x16x32_bf16 v[114:117], v[30:33], v[200:203], v[58:61]
	v_mfma_f32_16x16x32_bf16 v[58:61], v[148:151], v[196:199], v[94:97]
	v_mfma_f32_16x16x32_bf16 v[106:109], v[184:187], v[200:203], v[58:61]
	s_setprio 0
	s_barrier
	s_mov_b32 m0, s53
	s_nop 3
	v_lshl_add_u64 v[58:59], v[168:169], 0, s[86:87]
	ds_read_b128 v[78:81], v232
	ds_read_b128 v[82:85], v232 offset:1024
	ds_read_b128 v[228:231], v232 offset:2048
	ds_read_b128 v[232:235], v232 offset:3072
	global_load_lds_dwordx4 v[58:59], off
	v_lshl_add_u64 v[58:59], v[172:173], 0, s[86:87]
	s_mov_b32 m0, s52
	s_nop 0
	global_load_lds_dwordx4 v[58:59], off
	s_barrier
	s_waitcnt lgkmcnt(0)
	s_setprio 1
	s_waitcnt lgkmcnt(0)
	v_mfma_f32_16x16x32_bf16 v[34:37], v[228:231], v[50:53], v[34:37]
	v_mfma_f32_16x16x32_bf16 v[66:69], v[232:235], v[54:57], v[34:37]
	v_mfma_f32_16x16x32_bf16 v[34:37], v[78:81], v[98:101], v[38:41]
	v_mfma_f32_16x16x32_bf16 v[58:61], v[78:81], v[50:53], v[208:211]
	v_mfma_f32_16x16x32_bf16 v[50:53], v[82:85], v[102:105], v[34:37]
	v_mfma_f32_16x16x32_bf16 v[34:37], v[228:231], v[98:101], v[42:45]
	v_mfma_f32_16x16x32_bf16 v[58:61], v[82:85], v[54:57], v[58:61]
	v_mfma_f32_16x16x32_bf16 v[54:57], v[232:235], v[102:105], v[34:37]
	v_mfma_f32_16x16x32_bf16 v[34:37], v[78:81], v[110:113], v[46:49]
	v_mfma_f32_16x16x32_bf16 v[42:45], v[82:85], v[192:195], v[34:37]
	v_mfma_f32_16x16x32_bf16 v[34:37], v[228:231], v[110:113], v[136:139]
	v_mfma_f32_16x16x32_bf16 v[46:49], v[232:235], v[192:195], v[34:37]
	v_mfma_f32_16x16x32_bf16 v[34:37], v[78:81], v[196:199], v[140:143]
	v_mfma_f32_16x16x32_bf16 v[38:41], v[228:231], v[196:199], v[144:147]
	v_mfma_f32_16x16x32_bf16 v[34:37], v[82:85], v[200:203], v[34:37]
	v_mfma_f32_16x16x32_bf16 v[38:41], v[232:235], v[200:203], v[38:41]
	s_setprio 0
	s_mov_b32 m0, s45
	v_lshl_add_u64 v[70:71], v[240:241], 0, s[86:87]
	s_barrier
	ds_read_b128 v[136:139], v174 offset:49152
	ds_read_b128 v[140:143], v174 offset:50176
	ds_read_b128 v[144:147], v174 offset:51200
	ds_read_b128 v[192:195], v174 offset:52224
	ds_read_b128 v[196:199], v174 offset:53248
	ds_read_b128 v[200:203], v174 offset:54272
	ds_read_b128 v[208:211], v174 offset:55296
	ds_read_b128 v[236:239], v174 offset:56320
	global_load_lds_dwordx4 v[70:71], off
	v_lshl_add_u64 v[70:71], v[242:243], 0, s[86:87]
	s_mov_b32 m0, s46
	s_nop 0
	global_load_lds_dwordx4 v[70:71], off
	s_barrier
	s_waitcnt lgkmcnt(0)
	s_setprio 1
	s_waitcnt lgkmcnt(0)
	v_mfma_f32_16x16x32_bf16 v[70:73], v[26:29], v[136:139], v[152:155]
	v_mfma_f32_16x16x32_bf16 v[110:113], v[30:33], v[140:143], v[70:73]
	v_mfma_f32_16x16x32_bf16 v[70:73], v[148:151], v[136:139], v[156:159]
	v_mfma_f32_16x16x32_bf16 v[102:105], v[184:187], v[140:143], v[70:73]
	v_mfma_f32_16x16x32_bf16 v[70:73], v[26:29], v[144:147], v[160:163]
	v_mfma_f32_16x16x32_bf16 v[98:101], v[30:33], v[192:195], v[70:73]
	v_mfma_f32_16x16x32_bf16 v[70:73], v[148:151], v[144:147], v[164:167]
	v_mfma_f32_16x16x32_bf16 v[94:97], v[184:187], v[192:195], v[70:73]
	v_mfma_f32_16x16x32_bf16 v[70:73], v[26:29], v[196:199], v[176:179]
	v_mfma_f32_16x16x32_bf16 v[10:13], v[26:29], v[208:211], v[10:13]
	v_mfma_f32_16x16x32_bf16 v[90:93], v[30:33], v[200:203], v[70:73]
	v_mfma_f32_16x16x32_bf16 v[70:73], v[148:151], v[196:199], v[180:183]
	v_mfma_f32_16x16x32_bf16 v[74:77], v[30:33], v[236:239], v[10:13]
	v_mfma_f32_16x16x32_bf16 v[10:13], v[148:151], v[208:211], v[14:17]
	v_mfma_f32_16x16x32_bf16 v[86:89], v[184:187], v[200:203], v[70:73]
	v_mfma_f32_16x16x32_bf16 v[70:73], v[184:187], v[236:239], v[10:13]
	s_setprio 0
	s_barrier
	s_add_u32 s26, s30, 0x10080
	s_addc_u32 s27, s31, 0
	s_mov_b32 m0, s29
	s_nop 0
	v_lshl_add_u64 v[10:11], s[26:27], 0, v[0:1]
	global_load_lds_dwordx4 v[10:11], off
	v_lshl_add_u64 v[10:11], s[26:27], 0, v[134:135]
	s_mov_b32 m0, s28
	s_nop 0
	global_load_lds_dwordx4 v[10:11], off
	s_waitcnt vmcnt(6)
	s_barrier
; #define LAS __attribute__((address_space(3)))
; __device__ __forceinline__ unsigned cvt_pk_bf16(float lo, float hi) { unsigned r; asm volatile("v_cvt_pk_bf16_f32 %0, %1, %2" : "=v"(r) : "v"(lo), "v"(hi)); return r; }
; __device__ __forceinline__ int ltid(int sw) { unsigned z = 0u; asm volatile("" : "+s"(sw), "+s"(z)); int t = sw * 64 + (int)__builtin_amdgcn_mbcnt_hi(~0u, __builtin_amdgcn_mbcnt_lo(~0u, z)); asm volatile("" : "+v"(t)); return t; }
;     __device__ __forceinline__ void operator()(AccMut acc, const Unit& u, int sw) const {
;         const int tid_ = ltid(sw), lane_ = tid_ & 63, wr = sw >> 2, wc = sw & 3, fr = lane_ & 15, fq = lane_ >> 4;
;         const int row0 = u.pm * BM + wr * 64 + fr, c0 = u.pn * 128 + wc * 32 + 8 * fq;
;         u32x4 xnext = *(const u32x4*)(XC + (size_t)row0 * E + c0);
;         { f32x4 ns[2];
; #pragma unroll
;           for (int n = 0; n < 2; ++n) ns[n] = *(const LAS f32x4*)(nsp + c0 + 4 * n);
; #pragma unroll
;           for (int ai = 0; ai < 2; ++ai)
; #pragma unroll
;             for (int m = 0; m < 4; ++m) {
; #pragma unroll
;                 for (int n = 0; n < 2; ++n)
; #pragma unroll
;                     for (int jp = 0; jp < 2; ++jp) {
;                         const f32x2 z = (f32x2){acc[ai][0][m][n][2 * jp], acc[ai][0][m][n][2 * jp + 1]} * (-1.44269504f);
;                         f32x2 e; e.x = __builtin_amdgcn_exp2f(z.x); e.y = __builtin_amdgcn_exp2f(z.y); e = e + 1.0f;
;                         f32x2 r; r.x = __builtin_amdgcn_rcpf(e.x); r.y = __builtin_amdgcn_rcpf(e.y);
;                         r = r * (f32x2){ns[n][2 * jp], ns[n][2 * jp + 1]};
;                         acc[ai][0][m][n][2 * jp] = r.x; acc[ai][0][m][n][2 * jp + 1] = r.y; }
;                 const f32x4 l0 = acc[ai][0][m][0], l1 = acc[ai][0][m][1];
;                 u32x4 w; w.x = cvt_pk_bf16(l0[0], l0[1]); w.y = cvt_pk_bf16(l0[2], l0[3]); w.z = cvt_pk_bf16(l1[0], l1[1]); w.w = cvt_pk_bf16(l1[2], l1[3]);
;                 *(u32x4*)(LA + (size_t)(row0 + ai * HALF + m * 16) * E + c0) = w; } }
	s_setprio 1
	v_mfma_f32_16x16x32_bf16 v[10:13], v[78:81], v[136:139], v[18:21]
	v_mfma_f32_16x16x32_bf16 v[26:29], v[82:85], v[140:143], v[10:13]
	v_mfma_f32_16x16x32_bf16 v[10:13], v[228:231], v[136:139], v[22:25]
	v_mfma_f32_16x16x32_bf16 v[30:33], v[232:235], v[140:143], v[10:13]
	v_mfma_f32_16x16x32_bf16 v[10:13], v[78:81], v[144:147], v[188:191]
	v_mfma_f32_16x16x32_bf16 v[18:21], v[82:85], v[192:195], v[10:13]
	v_mfma_f32_16x16x32_bf16 v[10:13], v[228:231], v[144:147], v[212:215]
	v_mfma_f32_16x16x32_bf16 v[22:25], v[232:235], v[192:195], v[10:13]
	v_mfma_f32_16x16x32_bf16 v[10:13], v[78:81], v[196:199], v[62:65]
	v_mfma_f32_16x16x32_bf16 v[14:17], v[228:231], v[196:199], v[216:219]
	v_mfma_f32_16x16x32_bf16 v[2:5], v[78:81], v[208:211], v[2:5]
	v_mfma_f32_16x16x32_bf16 v[6:9], v[228:231], v[208:211], v[6:9]
	v_mfma_f32_16x16x32_bf16 v[10:13], v[82:85], v[200:203], v[10:13]
	v_mfma_f32_16x16x32_bf16 v[14:17], v[232:235], v[200:203], v[14:17]
	v_mfma_f32_16x16x32_bf16 v[2:5], v[82:85], v[236:239], v[2:5]
	v_mfma_f32_16x16x32_bf16 v[6:9], v[232:235], v[236:239], v[6:9]
	s_setprio 0
	s_barrier
	s_load_dwordx2 s[26:27], s[92:93], 0xa8
	v_mbcnt_lo_u32_b32 v216, -1, 0
	v_mbcnt_hi_u32_b32 v216, -1, v216
	v_mov_b32_e32 v237, 0x20000
	ds_read_b32 v239, v237 offset:48
	ds_read_b32 v237, v237 offset:40
	s_lshl_b32 s13, s24, 8
	s_add_i32 s13, s13, s3
	s_lshl_b32 s17, s22, 7
	s_or_b32 s17, s17, s85
	v_and_b32_e32 v217, 15, v216
	v_lshrrev_b32_e32 v218, 1, v216
	v_and_b32_e32 v218, 24, v218
	v_lshl_or_b32 v217, v217, 2, s13
	v_or_b32_e32 v219, s17, v218
	v_lshlrev_b32_e32 v168, 12, v217
	v_lshlrev_b32_e32 v240, 2, v219
	v_lshl_add_u32 v168, v219, 1, v168
	v_add_u32_e32 v240, 0x24400, v240
	global_load_dwordx4 v[136:139], v168, s[6:7] nt
	ds_read_b128 v[228:231], v240
	ds_read_b128 v[232:235], v240 offset:16
	v_add_u32_e32 v169, 0x1000, v168
	global_load_dwordx4 v[140:143], v169, s[6:7] nt
	v_add_u32_e32 v172, 0x2000, v168
	global_load_dwordx4 v[144:147], v172, s[6:7] nt
	v_add_u32_e32 v173, 0x3000, v168
	global_load_dwordx4 v[148:151], v173, s[6:7] nt
	v_add_u32_e32 v176, 0x80000, v168
	global_load_dwordx4 v[152:155], v176, s[6:7] nt
	v_add_u32_e32 v177, 0x81000, v168
	global_load_dwordx4 v[156:159], v177, s[6:7] nt
	v_add_u32_e32 v178, 0x82000, v168
	global_load_dwordx4 v[160:163], v178, s[6:7] nt
	v_add_u32_e32 v179, 0x83000, v168
	global_load_dwordx4 v[164:167], v179, s[6:7] nt
	s_lshl_b32 s17, s24, 2
	s_lshr_b32 s13, s3, 6
	s_add_i32 s17, s17, s13
	s_mov_b32 s24, 0xbe888889
	s_mov_b32 s22, 0xbfaaaaab
	s_mov_b32 s13, 0xbe000000
	v_mov_b32_e32 v236, 0xbf2aaaab
	v_mov_b32_e32 v238, 0
	s_waitcnt lgkmcnt(0)
	v_cmp_ne_u32_e32 vcc, 0, v239
	v_lshlrev_b32_e32 v237, 6, v237
	s_nop 0
	v_cndmask_b32_e32 v237, 0, v237, vcc
	v_add_u32_e32 v237, s17, v237
	v_lshl_add_u32 v237, v237, 11, v219
	v_lshlrev_b32_e32 v237, 2, v237
	v_add_u32_e32 v239, 0x800000, v237
	v_pk_mul_f32 v[180:181], v[204:205], s[74:75] op_sel_hi:[1,0]
	v_pk_mul_f32 v[182:183], v[206:207], s[74:75] op_sel_hi:[1,0]
	v_pk_mul_f32 v[184:185], v[220:221], s[74:75] op_sel_hi:[1,0]
	v_pk_mul_f32 v[186:187], v[222:223], s[74:75] op_sel_hi:[1,0]
	v_exp_f32_e32 v180, v180
	v_exp_f32_e32 v181, v181
	v_exp_f32_e32 v182, v182
	v_exp_f32_e32 v183, v183
	v_exp_f32_e32 v184, v184
	v_exp_f32_e32 v185, v185
	v_exp_f32_e32 v186, v186
	v_exp_f32_e32 v187, v187
	v_pk_add_f32 v[180:181], v[180:181], 1.0 op_sel_hi:[1,0]
	v_pk_add_f32 v[182:183], v[182:183], 1.0 op_sel_hi:[1,0]
	v_pk_add_f32 v[184:185], v[184:185], 1.0 op_sel_hi:[1,0]
	v_pk_add_f32 v[186:187], v[186:187], 1.0 op_sel_hi:[1,0]
	v_rcp_f32_e32 v180, v180
	v_rcp_f32_e32 v181, v181
	v_rcp_f32_e32 v182, v182
	v_rcp_f32_e32 v183, v183
	v_rcp_f32_e32 v184, v184
	v_rcp_f32_e32 v185, v185
	v_rcp_f32_e32 v186, v186
	v_rcp_f32_e32 v187, v187
	v_pk_mul_f32 v[204:205], v[180:181], v[228:229]
	v_pk_mul_f32 v[206:207], v[182:183], v[230:231]
	v_pk_mul_f32 v[220:221], v[184:185], v[232:233]
	v_pk_mul_f32 v[222:223], v[186:187], v[234:235]
	v_min3_f32 v238, v238, v204, v205
	v_min3_f32 v238, v238, v206, v207
	v_min3_f32 v238, v238, v220, v221
	v_min3_f32 v238, v238, v222, v223
	v_cvt_pk_bf16_f32 v208, v204, v205
	v_cvt_pk_bf16_f32 v209, v206, v207
	v_cvt_pk_bf16_f32 v210, v220, v221
	v_cvt_pk_bf16_f32 v211, v222, v223
	global_store_dwordx4 v168, v[208:211], s[8:9] nt
	v_pk_mul_f32 v[180:181], v[224:225], s[74:75] op_sel_hi:[1,0]
	v_pk_mul_f32 v[182:183], v[226:227], s[74:75] op_sel_hi:[1,0]
	v_pk_mul_f32 v[184:185], v[126:127], s[74:75] op_sel_hi:[1,0]
	v_pk_mul_f32 v[186:187], v[128:129], s[74:75] op_sel_hi:[1,0]
	v_exp_f32_e32 v180, v180
	v_exp_f32_e32 v181, v181
	v_exp_f32_e32 v182, v182
	v_exp_f32_e32 v183, v183
	v_exp_f32_e32 v184, v184
	v_exp_f32_e32 v185, v185
	v_exp_f32_e32 v186, v186
	v_exp_f32_e32 v187, v187
	v_pk_add_f32 v[180:181], v[180:181], 1.0 op_sel_hi:[1,0]
	v_pk_add_f32 v[182:183], v[182:183], 1.0 op_sel_hi:[1,0]
	v_pk_add_f32 v[184:185], v[184:185], 1.0 op_sel_hi:[1,0]
	v_pk_add_f32 v[186:187], v[186:187], 1.0 op_sel_hi:[1,0]
	v_rcp_f32_e32 v180, v180
	v_rcp_f32_e32 v181, v181
	v_rcp_f32_e32 v182, v182
	v_rcp_f32_e32 v183, v183
	v_rcp_f32_e32 v184, v184
	v_rcp_f32_e32 v185, v185
	v_rcp_f32_e32 v186, v186
	v_rcp_f32_e32 v187, v187
	v_pk_mul_f32 v[224:225], v[180:181], v[228:229]
	v_pk_mul_f32 v[226:227], v[182:183], v[230:231]
	v_pk_mul_f32 v[126:127], v[184:185], v[232:233]
	v_pk_mul_f32 v[128:129], v[186:187], v[234:235]
	v_min3_f32 v238, v238, v224, v225
	v_min3_f32 v238, v238, v226, v227
	v_min3_f32 v238, v238, v126, v127
	v_min3_f32 v238, v238, v128, v129
	v_cvt_pk_bf16_f32 v212, v224, v225
	v_cvt_pk_bf16_f32 v213, v226, v227
; __device__ __forceinline__ unsigned cvt_pk_bf16(float lo, float hi) { unsigned r; asm volatile("v_cvt_pk_bf16_f32 %0, %1, %2" : "=v"(r) : "v"(lo), "v"(hi)); return r; }
;     __device__ __forceinline__ void operator()(AccMut acc, const Unit& u, int sw) const {
;     ...
;           for (int ai = 0; ai < 2; ++ai)
; #pragma unroll
;             for (int m = 0; m < 4; ++m) {
; #pragma unroll
;                 for (int n = 0; n < 2; ++n)
; #pragma unroll
;                     for (int jp = 0; jp < 2; ++jp) {
;                         const f32x2 z = (f32x2){acc[ai][0][m][n][2 * jp], acc[ai][0][m][n][2 * jp + 1]} * (-1.44269504f);
;                         f32x2 e; e.x = __builtin_amdgcn_exp2f(z.x); e.y = __builtin_amdgcn_exp2f(z.y); e = e + 1.0f;
;                         f32x2 r; r.x = __builtin_amdgcn_rcpf(e.x); r.y = __builtin_amdgcn_rcpf(e.y);
;                         r = r * (f32x2){ns[n][2 * jp], ns[n][2 * jp + 1]};
;                         acc[ai][0][m][n][2 * jp] = r.x; acc[ai][0][m][n][2 * jp + 1] = r.y; }
;                 const f32x4 l0 = acc[ai][0][m][0], l1 = acc[ai][0][m][1];
;                 u32x4 w; w.x = cvt_pk_bf16(l0[0], l0[1]); w.y = cvt_pk_bf16(l0[2], l0[3]); w.z = cvt_pk_bf16(l1[0], l1[1]); w.w = cvt_pk_bf16(l1[2], l1[3]);
;                 *(u32x4*)(LA + (size_t)(row0 + ai * HALF + m * 16) * E + c0) = w; } }
	v_cvt_pk_bf16_f32 v214, v126, v127
	v_cvt_pk_bf16_f32 v215, v128, v129
	global_store_dwordx4 v169, v[212:215], s[8:9] nt
	v_pk_mul_f32 v[180:181], v[122:123], s[74:75] op_sel_hi:[1,0]
	v_pk_mul_f32 v[182:183], v[124:125], s[74:75] op_sel_hi:[1,0]
	v_pk_mul_f32 v[184:185], v[118:119], s[74:75] op_sel_hi:[1,0]
	v_pk_mul_f32 v[186:187], v[120:121], s[74:75] op_sel_hi:[1,0]
	v_exp_f32_e32 v180, v180
	v_exp_f32_e32 v181, v181
	v_exp_f32_e32 v182, v182
	v_exp_f32_e32 v183, v183
	v_exp_f32_e32 v184, v184
	v_exp_f32_e32 v185, v185
	v_exp_f32_e32 v186, v186
	v_exp_f32_e32 v187, v187
	v_pk_add_f32 v[180:181], v[180:181], 1.0 op_sel_hi:[1,0]
	v_pk_add_f32 v[182:183], v[182:183], 1.0 op_sel_hi:[1,0]
	v_pk_add_f32 v[184:185], v[184:185], 1.0 op_sel_hi:[1,0]
	v_pk_add_f32 v[186:187], v[186:187], 1.0 op_sel_hi:[1,0]
	v_rcp_f32_e32 v180, v180
	v_rcp_f32_e32 v181, v181
	v_rcp_f32_e32 v182, v182
	v_rcp_f32_e32 v183, v183
	v_rcp_f32_e32 v184, v184
	v_rcp_f32_e32 v185, v185
	v_rcp_f32_e32 v186, v186
	v_rcp_f32_e32 v187, v187
	v_pk_mul_f32 v[122:123], v[180:181], v[228:229]
	v_pk_mul_f32 v[124:125], v[182:183], v[230:231]
	v_pk_mul_f32 v[118:119], v[184:185], v[232:233]
	v_pk_mul_f32 v[120:121], v[186:187], v[234:235]
	v_min3_f32 v238, v238, v122, v123
	v_min3_f32 v238, v238, v124, v125
	v_min3_f32 v238, v238, v118, v119
	v_min3_f32 v238, v238, v120, v121
	v_cvt_pk_bf16_f32 v208, v122, v123
	v_cvt_pk_bf16_f32 v209, v124, v125
	v_cvt_pk_bf16_f32 v210, v118, v119
	v_cvt_pk_bf16_f32 v211, v120, v121
	global_store_dwordx4 v172, v[208:211], s[8:9] nt
	v_pk_mul_f32 v[180:181], v[114:115], s[74:75] op_sel_hi:[1,0]
	v_pk_mul_f32 v[182:183], v[116:117], s[74:75] op_sel_hi:[1,0]
	v_pk_mul_f32 v[184:185], v[106:107], s[74:75] op_sel_hi:[1,0]
	v_pk_mul_f32 v[186:187], v[108:109], s[74:75] op_sel_hi:[1,0]
	v_exp_f32_e32 v180, v180
	v_exp_f32_e32 v181, v181
	v_exp_f32_e32 v182, v182
	v_exp_f32_e32 v183, v183
	v_exp_f32_e32 v184, v184
	v_exp_f32_e32 v185, v185
	v_exp_f32_e32 v186, v186
	v_exp_f32_e32 v187, v187
	v_pk_add_f32 v[180:181], v[180:181], 1.0 op_sel_hi:[1,0]
	v_pk_add_f32 v[182:183], v[182:183], 1.0 op_sel_hi:[1,0]
	v_pk_add_f32 v[184:185], v[184:185], 1.0 op_sel_hi:[1,0]
	v_pk_add_f32 v[186:187], v[186:187], 1.0 op_sel_hi:[1,0]
	v_rcp_f32_e32 v180, v180
	v_rcp_f32_e32 v181, v181
	v_rcp_f32_e32 v182, v182
	v_rcp_f32_e32 v183, v183
	v_rcp_f32_e32 v184, v184
	v_rcp_f32_e32 v185, v185
	v_rcp_f32_e32 v186, v186
	v_rcp_f32_e32 v187, v187
	v_pk_mul_f32 v[114:115], v[180:181], v[228:229]
	v_pk_mul_f32 v[116:117], v[182:183], v[230:231]
	v_pk_mul_f32 v[106:107], v[184:185], v[232:233]
	v_pk_mul_f32 v[108:109], v[186:187], v[234:235]
	v_min3_f32 v238, v238, v114, v115
	v_min3_f32 v238, v238, v116, v117
	v_min3_f32 v238, v238, v106, v107
	v_min3_f32 v238, v238, v108, v109
	v_cvt_pk_bf16_f32 v212, v114, v115
	v_cvt_pk_bf16_f32 v213, v116, v117
	v_cvt_pk_bf16_f32 v214, v106, v107
	v_cvt_pk_bf16_f32 v215, v108, v109
	global_store_dwordx4 v173, v[212:215], s[8:9] nt
	v_pk_mul_f32 v[180:181], v[110:111], s[74:75] op_sel_hi:[1,0]
	v_pk_mul_f32 v[182:183], v[112:113], s[74:75] op_sel_hi:[1,0]
	v_pk_mul_f32 v[184:185], v[102:103], s[74:75] op_sel_hi:[1,0]
	v_pk_mul_f32 v[186:187], v[104:105], s[74:75] op_sel_hi:[1,0]
	v_exp_f32_e32 v180, v180
	v_exp_f32_e32 v181, v181
	v_exp_f32_e32 v182, v182
	v_exp_f32_e32 v183, v183
	v_exp_f32_e32 v184, v184
	v_exp_f32_e32 v185, v185
	v_exp_f32_e32 v186, v186
	v_exp_f32_e32 v187, v187
	v_pk_add_f32 v[180:181], v[180:181], 1.0 op_sel_hi:[1,0]
	v_pk_add_f32 v[182:183], v[182:183], 1.0 op_sel_hi:[1,0]
	v_pk_add_f32 v[184:185], v[184:185], 1.0 op_sel_hi:[1,0]
	v_pk_add_f32 v[186:187], v[186:187], 1.0 op_sel_hi:[1,0]
	v_rcp_f32_e32 v180, v180
	v_rcp_f32_e32 v181, v181
	v_rcp_f32_e32 v182, v182
	v_rcp_f32_e32 v183, v183
	v_rcp_f32_e32 v184, v184
	v_rcp_f32_e32 v185, v185
	v_rcp_f32_e32 v186, v186
	v_rcp_f32_e32 v187, v187
	v_pk_mul_f32 v[110:111], v[180:181], v[228:229]
	v_pk_mul_f32 v[112:113], v[182:183], v[230:231]
	v_pk_mul_f32 v[102:103], v[184:185], v[232:233]
	v_pk_mul_f32 v[104:105], v[186:187], v[234:235]
	v_min3_f32 v238, v238, v110, v111
	v_min3_f32 v238, v238, v112, v113
	v_min3_f32 v238, v238, v102, v103
	v_min3_f32 v238, v238, v104, v105
	v_cvt_pk_bf16_f32 v208, v110, v111
	v_cvt_pk_bf16_f32 v209, v112, v113
	v_cvt_pk_bf16_f32 v210, v102, v103
	v_cvt_pk_bf16_f32 v211, v104, v105
	global_store_dwordx4 v176, v[208:211], s[8:9] nt
	v_pk_mul_f32 v[180:181], v[98:99], s[74:75] op_sel_hi:[1,0]
	v_pk_mul_f32 v[182:183], v[100:101], s[74:75] op_sel_hi:[1,0]
	v_pk_mul_f32 v[184:185], v[94:95], s[74:75] op_sel_hi:[1,0]
	v_pk_mul_f32 v[186:187], v[96:97], s[74:75] op_sel_hi:[1,0]
	v_exp_f32_e32 v180, v180
	v_exp_f32_e32 v181, v181
	v_exp_f32_e32 v182, v182
	v_exp_f32_e32 v183, v183
	v_exp_f32_e32 v184, v184
	v_exp_f32_e32 v185, v185
	v_exp_f32_e32 v186, v186
	v_exp_f32_e32 v187, v187
	v_pk_add_f32 v[180:181], v[180:181], 1.0 op_sel_hi:[1,0]
	v_pk_add_f32 v[182:183], v[182:183], 1.0 op_sel_hi:[1,0]
	v_pk_add_f32 v[184:185], v[184:185], 1.0 op_sel_hi:[1,0]
	v_pk_add_f32 v[186:187], v[186:187], 1.0 op_sel_hi:[1,0]
	v_rcp_f32_e32 v180, v180
	v_rcp_f32_e32 v181, v181
	v_rcp_f32_e32 v182, v182
	v_rcp_f32_e32 v183, v183
	v_rcp_f32_e32 v184, v184
	v_rcp_f32_e32 v185, v185
	v_rcp_f32_e32 v186, v186
	v_rcp_f32_e32 v187, v187
	v_pk_mul_f32 v[98:99], v[180:181], v[228:229]
	v_pk_mul_f32 v[100:101], v[182:183], v[230:231]
	v_pk_mul_f32 v[94:95], v[184:185], v[232:233]
	v_pk_mul_f32 v[96:97], v[186:187], v[234:235]
	v_min3_f32 v238, v238, v98, v99
	v_min3_f32 v238, v238, v100, v101
	v_min3_f32 v238, v238, v94, v95
	v_min3_f32 v238, v238, v96, v97
;     __device__ __forceinline__ void operator()(AccMut acc, const Unit& u, int sw) const {
;     ...
;                         const f32x2 z = (f32x2){acc[ai][0][m][n][2 * jp], acc[ai][0][m][n][2 * jp + 1]} * (-1.44269504f);
;                         f32x2 e; e.x = __builtin_amdgcn_exp2f(z.x); e.y = __builtin_amdgcn_exp2f(z.y); e = e + 1.0f;
;                         f32x2 r; r.x = __builtin_amdgcn_rcpf(e.x); r.y = __builtin_amdgcn_rcpf(e.y);
;                         r = r * (f32x2){ns[n][2 * jp], ns[n][2 * jp + 1]};
;                         acc[ai][0][m][n][2 * jp] = r.x; acc[ai][0][m][n][2 * jp + 1] = r.y; }
;                 const f32x4 l0 = acc[ai][0][m][0], l1 = acc[ai][0][m][1];
;                 u32x4 w; w.x = cvt_pk_bf16(l0[0], l0[1]); w.y = cvt_pk_bf16(l0[2], l0[3]); w.z = cvt_pk_bf16(l1[0], l1[1]); w.w = cvt_pk_bf16(l1[2], l1[3]);
;                 *(u32x4*)(LA + (size_t)(row0 + ai * HALF + m * 16) * E + c0) = w; } }
;     ...
;                 float bt[8];
; #pragma unroll
;                 for (int n = 0; n < 2; ++n)
; #pragma unroll
;                     for (int jp = 0; jp < 2; ++jp) {
;                         const f32x2 z = (f32x2){acc[ai][1][m][n][2 * jp], acc[ai][1][m][n][2 * jp + 1]} * (-1.44269504f);
;                         f32x2 e; e.x = __builtin_amdgcn_exp2f(z.x); e.y = __builtin_amdgcn_exp2f(z.y); e = e + 1.0f;
;                         f32x2 ig; ig.x = __builtin_amdgcn_rcpf(e.x); ig.y = __builtin_amdgcn_rcpf(e.y);
;                         const f32x2 x2 = (f32x2){acc[ai][0][m][n][2 * jp], acc[ai][0][m][n][2 * jp + 1]} * 2.0f;
;                         f32x2 ser = x2 * (1.0f / 120.0f) + (1.0f / 24.0f); ser = ser * x2 + (1.0f / 6.0f); ser = ser * x2 + 0.5f; ser = ser * x2 + 1.0f; ser = ser * (-x2);
;                         f32x2 em = ser;
;                         if (__builtin_expect(__builtin_amdgcn_ballot_w64(x2.x <= -0.25f || x2.y <= -0.25f) != 0ull, 0)) {
;                             em.x = (x2.x > -0.25f) ? ser.x : (1.0f - fexp(x2.x)); em.y = (x2.y > -0.25f) ? ser.y : (1.0f - fexp(x2.y)); }
;                         const unsigned wv = xw[2 * n + jp];
;                         f32x2 sq; sq.x = __builtin_amdgcn_sqrtf(em.x); sq.y = __builtin_amdgcn_sqrtf(em.y);
;                         const f32x2 b2 = sq * ig * (f32x2){bf_lo(wv), bf_hi(wv)};
;                         bt[4 * n + 2 * jp] = b2.x; bt[4 * n + 2 * jp + 1] = b2.y; }
	v_cvt_pk_bf16_f32 v212, v98, v99
	v_cvt_pk_bf16_f32 v213, v100, v101
	v_cvt_pk_bf16_f32 v214, v94, v95
	v_cvt_pk_bf16_f32 v215, v96, v97
	global_store_dwordx4 v177, v[212:215], s[8:9] nt
	v_pk_mul_f32 v[180:181], v[90:91], s[74:75] op_sel_hi:[1,0]
	v_pk_mul_f32 v[182:183], v[92:93], s[74:75] op_sel_hi:[1,0]
	v_pk_mul_f32 v[184:185], v[86:87], s[74:75] op_sel_hi:[1,0]
	v_pk_mul_f32 v[186:187], v[88:89], s[74:75] op_sel_hi:[1,0]
	v_exp_f32_e32 v180, v180
	v_exp_f32_e32 v181, v181
	v_exp_f32_e32 v182, v182
	v_exp_f32_e32 v183, v183
	v_exp_f32_e32 v184, v184
	v_exp_f32_e32 v185, v185
	v_exp_f32_e32 v186, v186
	v_exp_f32_e32 v187, v187
	v_pk_add_f32 v[180:181], v[180:181], 1.0 op_sel_hi:[1,0]
	v_pk_add_f32 v[182:183], v[182:183], 1.0 op_sel_hi:[1,0]
	v_pk_add_f32 v[184:185], v[184:185], 1.0 op_sel_hi:[1,0]
	v_pk_add_f32 v[186:187], v[186:187], 1.0 op_sel_hi:[1,0]
	v_rcp_f32_e32 v180, v180
	v_rcp_f32_e32 v181, v181
	v_rcp_f32_e32 v182, v182
	v_rcp_f32_e32 v183, v183
	v_rcp_f32_e32 v184, v184
	v_rcp_f32_e32 v185, v185
	v_rcp_f32_e32 v186, v186
	v_rcp_f32_e32 v187, v187
	v_pk_mul_f32 v[90:91], v[180:181], v[228:229]
	v_pk_mul_f32 v[92:93], v[182:183], v[230:231]
	v_pk_mul_f32 v[86:87], v[184:185], v[232:233]
	v_pk_mul_f32 v[88:89], v[186:187], v[234:235]
	v_min3_f32 v238, v238, v90, v91
	v_min3_f32 v238, v238, v92, v93
	v_min3_f32 v238, v238, v86, v87
	v_min3_f32 v238, v238, v88, v89
	v_cvt_pk_bf16_f32 v208, v90, v91
	v_cvt_pk_bf16_f32 v209, v92, v93
	v_cvt_pk_bf16_f32 v210, v86, v87
	v_cvt_pk_bf16_f32 v211, v88, v89
	global_store_dwordx4 v178, v[208:211], s[8:9] nt
	v_pk_mul_f32 v[180:181], v[74:75], s[74:75] op_sel_hi:[1,0]
	v_pk_mul_f32 v[182:183], v[76:77], s[74:75] op_sel_hi:[1,0]
	v_pk_mul_f32 v[184:185], v[70:71], s[74:75] op_sel_hi:[1,0]
	v_pk_mul_f32 v[186:187], v[72:73], s[74:75] op_sel_hi:[1,0]
	v_exp_f32_e32 v180, v180
	v_exp_f32_e32 v181, v181
	v_exp_f32_e32 v182, v182
	v_exp_f32_e32 v183, v183
	v_exp_f32_e32 v184, v184
	v_exp_f32_e32 v185, v185
	v_exp_f32_e32 v186, v186
	v_exp_f32_e32 v187, v187
	v_pk_add_f32 v[180:181], v[180:181], 1.0 op_sel_hi:[1,0]
	v_pk_add_f32 v[182:183], v[182:183], 1.0 op_sel_hi:[1,0]
	v_pk_add_f32 v[184:185], v[184:185], 1.0 op_sel_hi:[1,0]
	v_pk_add_f32 v[186:187], v[186:187], 1.0 op_sel_hi:[1,0]
	v_rcp_f32_e32 v180, v180
	v_rcp_f32_e32 v181, v181
	v_rcp_f32_e32 v182, v182
	v_rcp_f32_e32 v183, v183
	v_rcp_f32_e32 v184, v184
	v_rcp_f32_e32 v185, v185
	v_rcp_f32_e32 v186, v186
	v_rcp_f32_e32 v187, v187
	v_pk_mul_f32 v[74:75], v[180:181], v[228:229]
	v_pk_mul_f32 v[76:77], v[182:183], v[230:231]
	v_pk_mul_f32 v[70:71], v[184:185], v[232:233]
	v_pk_mul_f32 v[72:73], v[186:187], v[234:235]
	v_min3_f32 v238, v238, v74, v75
	v_min3_f32 v238, v238, v76, v77
	v_min3_f32 v238, v238, v70, v71
	v_min3_f32 v238, v238, v72, v73
	v_cvt_pk_bf16_f32 v212, v74, v75
	v_cvt_pk_bf16_f32 v213, v76, v77
	v_cvt_pk_bf16_f32 v214, v70, v71
	v_cvt_pk_bf16_f32 v215, v72, v73
	global_store_dwordx4 v179, v[212:215], s[8:9] nt
	v_cmp_ge_f32_e32 vcc, s13, v238
	s_nop 4
	s_cbranch_vccnz .Lgate_epi_general
	v_pk_mul_f32 v[180:181], v[58:59], s[74:75] op_sel_hi:[1,0]
	v_pk_mul_f32 v[182:183], v[60:61], s[74:75] op_sel_hi:[1,0]
	v_pk_mul_f32 v[184:185], v[66:67], s[74:75] op_sel_hi:[1,0]
	v_pk_mul_f32 v[186:187], v[68:69], s[74:75] op_sel_hi:[1,0]
	v_exp_f32_e32 v180, v180
	v_exp_f32_e32 v181, v181
	v_exp_f32_e32 v182, v182
	v_exp_f32_e32 v183, v183
	v_exp_f32_e32 v184, v184
	v_exp_f32_e32 v185, v185
	v_exp_f32_e32 v186, v186
	v_exp_f32_e32 v187, v187
	v_pk_fma_f32 v[188:189], v[204:205], s[24:25], v[236:237] op_sel_hi:[1,0,0]
	v_pk_fma_f32 v[190:191], v[206:207], s[24:25], v[236:237] op_sel_hi:[1,0,0]
	v_pk_fma_f32 v[192:193], v[220:221], s[24:25], v[236:237] op_sel_hi:[1,0,0]
	v_pk_fma_f32 v[194:195], v[222:223], s[24:25], v[236:237] op_sel_hi:[1,0,0]
	v_pk_add_f32 v[180:181], v[180:181], 1.0 op_sel_hi:[1,0]
	v_pk_add_f32 v[182:183], v[182:183], 1.0 op_sel_hi:[1,0]
	v_pk_add_f32 v[184:185], v[184:185], 1.0 op_sel_hi:[1,0]
	v_pk_add_f32 v[186:187], v[186:187], 1.0 op_sel_hi:[1,0]
	v_rcp_f32_e32 v180, v180
	v_rcp_f32_e32 v181, v181
	v_rcp_f32_e32 v182, v182
	v_rcp_f32_e32 v183, v183
	v_rcp_f32_e32 v184, v184
	v_rcp_f32_e32 v185, v185
	v_rcp_f32_e32 v186, v186
	v_rcp_f32_e32 v187, v187
	v_pk_fma_f32 v[188:189], v[204:205], v[188:189], s[22:23] op_sel_hi:[1,1,0]
	v_pk_fma_f32 v[190:191], v[206:207], v[190:191], s[22:23] op_sel_hi:[1,1,0]
	v_pk_fma_f32 v[192:193], v[220:221], v[192:193], s[22:23] op_sel_hi:[1,1,0]
	v_pk_fma_f32 v[194:195], v[222:223], v[194:195], s[22:23] op_sel_hi:[1,1,0]
	v_pk_fma_f32 v[188:189], v[204:205], v[188:189], -2.0 op_sel_hi:[1,1,0]
	v_pk_fma_f32 v[190:191], v[206:207], v[190:191], -2.0 op_sel_hi:[1,1,0]
	v_pk_fma_f32 v[192:193], v[220:221], v[192:193], -2.0 op_sel_hi:[1,1,0]
	v_pk_fma_f32 v[194:195], v[222:223], v[194:195], -2.0 op_sel_hi:[1,1,0]
	v_pk_fma_f32 v[188:189], v[204:205], v[188:189], -2.0 op_sel_hi:[1,1,0]
	v_pk_fma_f32 v[190:191], v[206:207], v[190:191], -2.0 op_sel_hi:[1,1,0]
	v_pk_fma_f32 v[192:193], v[220:221], v[192:193], -2.0 op_sel_hi:[1,1,0]
	v_pk_fma_f32 v[194:195], v[222:223], v[194:195], -2.0 op_sel_hi:[1,1,0]
	v_pk_mul_f32 v[188:189], v[204:205], v[188:189]
	v_pk_mul_f32 v[190:191], v[206:207], v[190:191]
	v_pk_mul_f32 v[192:193], v[220:221], v[192:193]
	v_pk_mul_f32 v[194:195], v[222:223], v[194:195]
	v_pk_mul_f32 v[228:229], v[204:205], s[74:75] op_sel_hi:[1,0] neg_lo:[0,1] neg_hi:[0,1]
	v_pk_mul_f32 v[230:231], v[206:207], s[74:75] op_sel_hi:[1,0] neg_lo:[0,1] neg_hi:[0,1]
	v_pk_mul_f32 v[232:233], v[220:221], s[74:75] op_sel_hi:[1,0] neg_lo:[0,1] neg_hi:[0,1]
	v_pk_mul_f32 v[234:235], v[222:223], s[74:75] op_sel_hi:[1,0] neg_lo:[0,1] neg_hi:[0,1]
	v_sqrt_f32_e32 v188, v188
	v_sqrt_f32_e32 v189, v189
	v_sqrt_f32_e32 v190, v190
	v_sqrt_f32_e32 v191, v191
	v_sqrt_f32_e32 v192, v192
	v_sqrt_f32_e32 v193, v193
	v_sqrt_f32_e32 v194, v194
	v_sqrt_f32_e32 v195, v195
	v_exp_f32_e32 v58, v228
	v_exp_f32_e32 v59, v229
	v_exp_f32_e32 v60, v230
	v_exp_f32_e32 v61, v231
	v_exp_f32_e32 v66, v232
	v_exp_f32_e32 v67, v233
	v_exp_f32_e32 v68, v234
	v_exp_f32_e32 v69, v235
	s_waitcnt vmcnt(15)
; __device__ __forceinline__ unsigned cvt_pk_bf16(float lo, float hi) { unsigned r; asm volatile("v_cvt_pk_bf16_f32 %0, %1, %2" : "=v"(r) : "v"(lo), "v"(hi)); return r; }
;     __device__ __forceinline__ void operator()(AccMut acc, const Unit& u, int sw) const {
;     ...
;                 for (int n = 0; n < 2; ++n)
; #pragma unroll
;                     for (int jp = 0; jp < 2; ++jp) {
;                         const f32x2 z = (f32x2){acc[ai][1][m][n][2 * jp], acc[ai][1][m][n][2 * jp + 1]} * (-1.44269504f);
;                         f32x2 e; e.x = __builtin_amdgcn_exp2f(z.x); e.y = __builtin_amdgcn_exp2f(z.y); e = e + 1.0f;
;                         f32x2 ig; ig.x = __builtin_amdgcn_rcpf(e.x); ig.y = __builtin_amdgcn_rcpf(e.y);
;                         const f32x2 x2 = (f32x2){acc[ai][0][m][n][2 * jp], acc[ai][0][m][n][2 * jp + 1]} * 2.0f;
;                         f32x2 ser = x2 * (1.0f / 120.0f) + (1.0f / 24.0f); ser = ser * x2 + (1.0f / 6.0f); ser = ser * x2 + 0.5f; ser = ser * x2 + 1.0f; ser = ser * (-x2);
;                         f32x2 em = ser;
;                         if (__builtin_expect(__builtin_amdgcn_ballot_w64(x2.x <= -0.25f || x2.y <= -0.25f) != 0ull, 0)) {
;                             em.x = (x2.x > -0.25f) ? ser.x : (1.0f - fexp(x2.x)); em.y = (x2.y > -0.25f) ? ser.y : (1.0f - fexp(x2.y)); }
;                         const unsigned wv = xw[2 * n + jp];
;                         f32x2 sq; sq.x = __builtin_amdgcn_sqrtf(em.x); sq.y = __builtin_amdgcn_sqrtf(em.y);
;                         const f32x2 b2 = sq * ig * (f32x2){bf_lo(wv), bf_hi(wv)};
;                         bt[4 * n + 2 * jp] = b2.x; bt[4 * n + 2 * jp + 1] = b2.y; }
;                 u32x4 w; w.x = cvt_pk_bf16(bt[0], bt[1]); w.y = cvt_pk_bf16(bt[2], bt[3]); w.z = cvt_pk_bf16(bt[4], bt[5]); w.w = cvt_pk_bf16(bt[6], bt[7]);
;                 *(u32x4*)(BT + off) = w; }
; __device__ __forceinline__ void scan1_phase(const bf16_t* LA, const bf16_t* BT, int sw, View vw) {
;     ...
;             for (int i = 0; i < 8; ++i) {
;                 const float l0 = bf_lo(lw[i].x), l1 = bf_hi(lw[i].x), l2 = bf_lo(lw[i].y), l3 = bf_hi(lw[i].y);
;                 S[0] += l0; S[1] += l1; S[2] += l2; S[3] += l3;
;                 Hc[0] = fexp(l0) * Hc[0] + bf_lo(bw[i].x); Hc[1] = fexp(l1) * Hc[1] + bf_hi(bw[i].x); Hc[2] = fexp(l2) * Hc[2] + bf_lo(bw[i].y); Hc[3] = fexp(l3) * Hc[3] + bf_hi(bw[i].y); }
	v_lshlrev_b32_e32 v196, 16, v136
	v_and_b32_e32 v197, 0xffff0000, v136
	v_lshlrev_b32_e32 v198, 16, v137
	v_and_b32_e32 v199, 0xffff0000, v137
	v_lshlrev_b32_e32 v200, 16, v138
	v_and_b32_e32 v201, 0xffff0000, v138
	v_lshlrev_b32_e32 v202, 16, v139
	v_and_b32_e32 v203, 0xffff0000, v139
	v_pk_mul_f32 v[188:189], v[188:189], v[180:181]
	v_pk_mul_f32 v[190:191], v[190:191], v[182:183]
	v_pk_mul_f32 v[192:193], v[192:193], v[184:185]
	v_pk_mul_f32 v[194:195], v[194:195], v[186:187]
	v_pk_mul_f32 v[216:217], v[188:189], v[196:197]
	v_pk_mul_f32 v[218:219], v[190:191], v[198:199]
	v_pk_mul_f32 v[240:241], v[192:193], v[200:201]
	v_pk_mul_f32 v[242:243], v[194:195], v[202:203]
	v_cvt_pk_bf16_f32 v208, v216, v217
	v_cvt_pk_bf16_f32 v209, v218, v219
	v_cvt_pk_bf16_f32 v210, v240, v241
	v_cvt_pk_bf16_f32 v211, v242, v243
	global_store_dwordx4 v168, v[208:211], s[10:11] nt
	v_pk_mul_f32 v[180:181], v[50:51], s[74:75] op_sel_hi:[1,0]
	v_pk_mul_f32 v[182:183], v[52:53], s[74:75] op_sel_hi:[1,0]
	v_pk_mul_f32 v[184:185], v[54:55], s[74:75] op_sel_hi:[1,0]
	v_pk_mul_f32 v[186:187], v[56:57], s[74:75] op_sel_hi:[1,0]
	v_exp_f32_e32 v180, v180
	v_exp_f32_e32 v181, v181
	v_exp_f32_e32 v182, v182
	v_exp_f32_e32 v183, v183
	v_exp_f32_e32 v184, v184
	v_exp_f32_e32 v185, v185
	v_exp_f32_e32 v186, v186
	v_exp_f32_e32 v187, v187
	v_pk_fma_f32 v[188:189], v[224:225], s[24:25], v[236:237] op_sel_hi:[1,0,0]
	v_pk_fma_f32 v[190:191], v[226:227], s[24:25], v[236:237] op_sel_hi:[1,0,0]
	v_pk_fma_f32 v[192:193], v[126:127], s[24:25], v[236:237] op_sel_hi:[1,0,0]
	v_pk_fma_f32 v[194:195], v[128:129], s[24:25], v[236:237] op_sel_hi:[1,0,0]
	v_pk_add_f32 v[180:181], v[180:181], 1.0 op_sel_hi:[1,0]
	v_pk_add_f32 v[182:183], v[182:183], 1.0 op_sel_hi:[1,0]
	v_pk_add_f32 v[184:185], v[184:185], 1.0 op_sel_hi:[1,0]
	v_pk_add_f32 v[186:187], v[186:187], 1.0 op_sel_hi:[1,0]
	v_rcp_f32_e32 v180, v180
	v_rcp_f32_e32 v181, v181
	v_rcp_f32_e32 v182, v182
	v_rcp_f32_e32 v183, v183
	v_rcp_f32_e32 v184, v184
	v_rcp_f32_e32 v185, v185
	v_rcp_f32_e32 v186, v186
	v_rcp_f32_e32 v187, v187
	v_pk_fma_f32 v[188:189], v[224:225], v[188:189], s[22:23] op_sel_hi:[1,1,0]
	v_pk_fma_f32 v[190:191], v[226:227], v[190:191], s[22:23] op_sel_hi:[1,1,0]
	v_pk_fma_f32 v[192:193], v[126:127], v[192:193], s[22:23] op_sel_hi:[1,1,0]
	v_pk_fma_f32 v[194:195], v[128:129], v[194:195], s[22:23] op_sel_hi:[1,1,0]
	v_pk_fma_f32 v[188:189], v[224:225], v[188:189], -2.0 op_sel_hi:[1,1,0]
	v_pk_fma_f32 v[190:191], v[226:227], v[190:191], -2.0 op_sel_hi:[1,1,0]
	v_pk_fma_f32 v[192:193], v[126:127], v[192:193], -2.0 op_sel_hi:[1,1,0]
	v_pk_fma_f32 v[194:195], v[128:129], v[194:195], -2.0 op_sel_hi:[1,1,0]
	v_pk_fma_f32 v[188:189], v[224:225], v[188:189], -2.0 op_sel_hi:[1,1,0]
	v_pk_fma_f32 v[190:191], v[226:227], v[190:191], -2.0 op_sel_hi:[1,1,0]
	v_pk_fma_f32 v[192:193], v[126:127], v[192:193], -2.0 op_sel_hi:[1,1,0]
	v_pk_fma_f32 v[194:195], v[128:129], v[194:195], -2.0 op_sel_hi:[1,1,0]
	v_pk_mul_f32 v[188:189], v[224:225], v[188:189]
	v_pk_mul_f32 v[190:191], v[226:227], v[190:191]
	v_pk_mul_f32 v[192:193], v[126:127], v[192:193]
	v_pk_mul_f32 v[194:195], v[128:129], v[194:195]
	v_pk_mul_f32 v[228:229], v[224:225], s[74:75] op_sel_hi:[1,0] neg_lo:[0,1] neg_hi:[0,1]
	v_pk_mul_f32 v[230:231], v[226:227], s[74:75] op_sel_hi:[1,0] neg_lo:[0,1] neg_hi:[0,1]
	v_pk_mul_f32 v[232:233], v[126:127], s[74:75] op_sel_hi:[1,0] neg_lo:[0,1] neg_hi:[0,1]
	v_pk_mul_f32 v[234:235], v[128:129], s[74:75] op_sel_hi:[1,0] neg_lo:[0,1] neg_hi:[0,1]
	v_sqrt_f32_e32 v188, v188
	v_sqrt_f32_e32 v189, v189
	v_sqrt_f32_e32 v190, v190
	v_sqrt_f32_e32 v191, v191
	v_sqrt_f32_e32 v192, v192
	v_sqrt_f32_e32 v193, v193
	v_sqrt_f32_e32 v194, v194
	v_sqrt_f32_e32 v195, v195
	v_exp_f32_e32 v228, v228
	v_exp_f32_e32 v229, v229
	v_exp_f32_e32 v230, v230
	v_exp_f32_e32 v231, v231
	v_exp_f32_e32 v232, v232
	v_exp_f32_e32 v233, v233
	v_exp_f32_e32 v234, v234
	v_exp_f32_e32 v235, v235
	s_waitcnt vmcnt(15)
	v_lshlrev_b32_e32 v196, 16, v140
	v_and_b32_e32 v197, 0xffff0000, v140
	v_lshlrev_b32_e32 v198, 16, v141
	v_and_b32_e32 v199, 0xffff0000, v141
	v_lshlrev_b32_e32 v200, 16, v142
	v_and_b32_e32 v201, 0xffff0000, v142
	v_lshlrev_b32_e32 v202, 16, v143
	v_and_b32_e32 v203, 0xffff0000, v143
	v_pk_mul_f32 v[188:189], v[188:189], v[180:181]
	v_pk_mul_f32 v[190:191], v[190:191], v[182:183]
	v_pk_mul_f32 v[192:193], v[192:193], v[184:185]
	v_pk_mul_f32 v[194:195], v[194:195], v[186:187]
	v_pk_mul_f32 v[188:189], v[188:189], v[196:197]
	v_pk_mul_f32 v[190:191], v[190:191], v[198:199]
	v_pk_mul_f32 v[192:193], v[192:193], v[200:201]
	v_pk_mul_f32 v[194:195], v[194:195], v[202:203]
	v_cvt_pk_bf16_f32 v212, v188, v189
	v_cvt_pk_bf16_f32 v213, v190, v191
	v_cvt_pk_bf16_f32 v214, v192, v193
	v_cvt_pk_bf16_f32 v215, v194, v195
	global_store_dwordx4 v169, v[212:215], s[10:11] nt
	v_pk_fma_f32 v[216:217], v[228:229], v[216:217], v[188:189]
	v_pk_fma_f32 v[218:219], v[230:231], v[218:219], v[190:191]
	v_pk_fma_f32 v[240:241], v[232:233], v[240:241], v[192:193]
	v_pk_fma_f32 v[242:243], v[234:235], v[242:243], v[194:195]
	v_pk_mul_f32 v[58:59], v[58:59], v[228:229]
	v_pk_mul_f32 v[60:61], v[60:61], v[230:231]
	v_pk_mul_f32 v[66:67], v[66:67], v[232:233]
	v_pk_mul_f32 v[68:69], v[68:69], v[234:235]
	v_pk_add_f32 v[204:205], v[204:205], v[224:225]
	v_pk_add_f32 v[206:207], v[206:207], v[226:227]
	v_pk_add_f32 v[220:221], v[220:221], v[126:127]
	v_pk_add_f32 v[222:223], v[222:223], v[128:129]
	v_pk_mul_f32 v[180:181], v[42:43], s[74:75] op_sel_hi:[1,0]
	v_pk_mul_f32 v[182:183], v[44:45], s[74:75] op_sel_hi:[1,0]
	v_pk_mul_f32 v[184:185], v[46:47], s[74:75] op_sel_hi:[1,0]
; __device__ __forceinline__ unsigned cvt_pk_bf16(float lo, float hi) { unsigned r; asm volatile("v_cvt_pk_bf16_f32 %0, %1, %2" : "=v"(r) : "v"(lo), "v"(hi)); return r; }
;     __device__ __forceinline__ void operator()(AccMut acc, const Unit& u, int sw) const {
;     ...
;                 for (int n = 0; n < 2; ++n)
; #pragma unroll
;                     for (int jp = 0; jp < 2; ++jp) {
;                         const f32x2 z = (f32x2){acc[ai][1][m][n][2 * jp], acc[ai][1][m][n][2 * jp + 1]} * (-1.44269504f);
;                         f32x2 e; e.x = __builtin_amdgcn_exp2f(z.x); e.y = __builtin_amdgcn_exp2f(z.y); e = e + 1.0f;
;                         f32x2 ig; ig.x = __builtin_amdgcn_rcpf(e.x); ig.y = __builtin_amdgcn_rcpf(e.y);
;                         const f32x2 x2 = (f32x2){acc[ai][0][m][n][2 * jp], acc[ai][0][m][n][2 * jp + 1]} * 2.0f;
;                         f32x2 ser = x2 * (1.0f / 120.0f) + (1.0f / 24.0f); ser = ser * x2 + (1.0f / 6.0f); ser = ser * x2 + 0.5f; ser = ser * x2 + 1.0f; ser = ser * (-x2);
;                         f32x2 em = ser;
;                         if (__builtin_expect(__builtin_amdgcn_ballot_w64(x2.x <= -0.25f || x2.y <= -0.25f) != 0ull, 0)) {
;                             em.x = (x2.x > -0.25f) ? ser.x : (1.0f - fexp(x2.x)); em.y = (x2.y > -0.25f) ? ser.y : (1.0f - fexp(x2.y)); }
;                         const unsigned wv = xw[2 * n + jp];
;                         f32x2 sq; sq.x = __builtin_amdgcn_sqrtf(em.x); sq.y = __builtin_amdgcn_sqrtf(em.y);
;                         const f32x2 b2 = sq * ig * (f32x2){bf_lo(wv), bf_hi(wv)};
;                         bt[4 * n + 2 * jp] = b2.x; bt[4 * n + 2 * jp + 1] = b2.y; }
;                 u32x4 w; w.x = cvt_pk_bf16(bt[0], bt[1]); w.y = cvt_pk_bf16(bt[2], bt[3]); w.z = cvt_pk_bf16(bt[4], bt[5]); w.w = cvt_pk_bf16(bt[6], bt[7]);
;                 *(u32x4*)(BT + off) = w; }
; __device__ __forceinline__ void scan1_phase(const bf16_t* LA, const bf16_t* BT, int sw, View vw) {
;     ...
;             for (int i = 0; i < 8; ++i) {
;                 const float l0 = bf_lo(lw[i].x), l1 = bf_hi(lw[i].x), l2 = bf_lo(lw[i].y), l3 = bf_hi(lw[i].y);
;                 S[0] += l0; S[1] += l1; S[2] += l2; S[3] += l3;
;                 Hc[0] = fexp(l0) * Hc[0] + bf_lo(bw[i].x); Hc[1] = fexp(l1) * Hc[1] + bf_hi(bw[i].x); Hc[2] = fexp(l2) * Hc[2] + bf_lo(bw[i].y); Hc[3] = fexp(l3) * Hc[3] + bf_hi(bw[i].y); }
	v_pk_mul_f32 v[186:187], v[48:49], s[74:75] op_sel_hi:[1,0]
	v_exp_f32_e32 v180, v180
	v_exp_f32_e32 v181, v181
	v_exp_f32_e32 v182, v182
	v_exp_f32_e32 v183, v183
	v_exp_f32_e32 v184, v184
	v_exp_f32_e32 v185, v185
	v_exp_f32_e32 v186, v186
	v_exp_f32_e32 v187, v187
	v_pk_fma_f32 v[188:189], v[122:123], s[24:25], v[236:237] op_sel_hi:[1,0,0]
	v_pk_fma_f32 v[190:191], v[124:125], s[24:25], v[236:237] op_sel_hi:[1,0,0]
	v_pk_fma_f32 v[192:193], v[118:119], s[24:25], v[236:237] op_sel_hi:[1,0,0]
	v_pk_fma_f32 v[194:195], v[120:121], s[24:25], v[236:237] op_sel_hi:[1,0,0]
	v_pk_add_f32 v[180:181], v[180:181], 1.0 op_sel_hi:[1,0]
	v_pk_add_f32 v[182:183], v[182:183], 1.0 op_sel_hi:[1,0]
	v_pk_add_f32 v[184:185], v[184:185], 1.0 op_sel_hi:[1,0]
	v_pk_add_f32 v[186:187], v[186:187], 1.0 op_sel_hi:[1,0]
	v_rcp_f32_e32 v180, v180
	v_rcp_f32_e32 v181, v181
	v_rcp_f32_e32 v182, v182
	v_rcp_f32_e32 v183, v183
	v_rcp_f32_e32 v184, v184
	v_rcp_f32_e32 v185, v185
	v_rcp_f32_e32 v186, v186
	v_rcp_f32_e32 v187, v187
	v_pk_fma_f32 v[188:189], v[122:123], v[188:189], s[22:23] op_sel_hi:[1,1,0]
	v_pk_fma_f32 v[190:191], v[124:125], v[190:191], s[22:23] op_sel_hi:[1,1,0]
	v_pk_fma_f32 v[192:193], v[118:119], v[192:193], s[22:23] op_sel_hi:[1,1,0]
	v_pk_fma_f32 v[194:195], v[120:121], v[194:195], s[22:23] op_sel_hi:[1,1,0]
	v_pk_fma_f32 v[188:189], v[122:123], v[188:189], -2.0 op_sel_hi:[1,1,0]
	v_pk_fma_f32 v[190:191], v[124:125], v[190:191], -2.0 op_sel_hi:[1,1,0]
	v_pk_fma_f32 v[192:193], v[118:119], v[192:193], -2.0 op_sel_hi:[1,1,0]
	v_pk_fma_f32 v[194:195], v[120:121], v[194:195], -2.0 op_sel_hi:[1,1,0]
	v_pk_fma_f32 v[188:189], v[122:123], v[188:189], -2.0 op_sel_hi:[1,1,0]
	v_pk_fma_f32 v[190:191], v[124:125], v[190:191], -2.0 op_sel_hi:[1,1,0]
	v_pk_fma_f32 v[192:193], v[118:119], v[192:193], -2.0 op_sel_hi:[1,1,0]
	v_pk_fma_f32 v[194:195], v[120:121], v[194:195], -2.0 op_sel_hi:[1,1,0]
	v_pk_mul_f32 v[188:189], v[122:123], v[188:189]
	v_pk_mul_f32 v[190:191], v[124:125], v[190:191]
	v_pk_mul_f32 v[192:193], v[118:119], v[192:193]
	v_pk_mul_f32 v[194:195], v[120:121], v[194:195]
	v_pk_mul_f32 v[228:229], v[122:123], s[74:75] op_sel_hi:[1,0] neg_lo:[0,1] neg_hi:[0,1]
	v_pk_mul_f32 v[230:231], v[124:125], s[74:75] op_sel_hi:[1,0] neg_lo:[0,1] neg_hi:[0,1]
	v_pk_mul_f32 v[232:233], v[118:119], s[74:75] op_sel_hi:[1,0] neg_lo:[0,1] neg_hi:[0,1]
	v_pk_mul_f32 v[234:235], v[120:121], s[74:75] op_sel_hi:[1,0] neg_lo:[0,1] neg_hi:[0,1]
	v_sqrt_f32_e32 v188, v188
	v_sqrt_f32_e32 v189, v189
	v_sqrt_f32_e32 v190, v190
	v_sqrt_f32_e32 v191, v191
	v_sqrt_f32_e32 v192, v192
	v_sqrt_f32_e32 v193, v193
	v_sqrt_f32_e32 v194, v194
	v_sqrt_f32_e32 v195, v195
	v_exp_f32_e32 v228, v228
	v_exp_f32_e32 v229, v229
	v_exp_f32_e32 v230, v230
	v_exp_f32_e32 v231, v231
	v_exp_f32_e32 v232, v232
	v_exp_f32_e32 v233, v233
	v_exp_f32_e32 v234, v234
	v_exp_f32_e32 v235, v235
	s_waitcnt vmcnt(15)
	v_lshlrev_b32_e32 v196, 16, v144
	v_and_b32_e32 v197, 0xffff0000, v144
	v_lshlrev_b32_e32 v198, 16, v145
	v_and_b32_e32 v199, 0xffff0000, v145
	v_lshlrev_b32_e32 v200, 16, v146
	v_and_b32_e32 v201, 0xffff0000, v146
	v_lshlrev_b32_e32 v202, 16, v147
	v_and_b32_e32 v203, 0xffff0000, v147
	v_pk_mul_f32 v[188:189], v[188:189], v[180:181]
	v_pk_mul_f32 v[190:191], v[190:191], v[182:183]
	v_pk_mul_f32 v[192:193], v[192:193], v[184:185]
	v_pk_mul_f32 v[194:195], v[194:195], v[186:187]
	v_pk_mul_f32 v[188:189], v[188:189], v[196:197]
	v_pk_mul_f32 v[190:191], v[190:191], v[198:199]
	v_pk_mul_f32 v[192:193], v[192:193], v[200:201]
	v_pk_mul_f32 v[194:195], v[194:195], v[202:203]
	v_cvt_pk_bf16_f32 v208, v188, v189
	v_cvt_pk_bf16_f32 v209, v190, v191
	v_cvt_pk_bf16_f32 v210, v192, v193
	v_cvt_pk_bf16_f32 v211, v194, v195
	global_store_dwordx4 v172, v[208:211], s[10:11] nt
	v_pk_fma_f32 v[216:217], v[228:229], v[216:217], v[188:189]
	v_pk_fma_f32 v[218:219], v[230:231], v[218:219], v[190:191]
	v_pk_fma_f32 v[240:241], v[232:233], v[240:241], v[192:193]
	v_pk_fma_f32 v[242:243], v[234:235], v[242:243], v[194:195]
	v_pk_mul_f32 v[58:59], v[58:59], v[228:229]
	v_pk_mul_f32 v[60:61], v[60:61], v[230:231]
	v_pk_mul_f32 v[66:67], v[66:67], v[232:233]
	v_pk_mul_f32 v[68:69], v[68:69], v[234:235]
	v_pk_add_f32 v[204:205], v[204:205], v[122:123]
	v_pk_add_f32 v[206:207], v[206:207], v[124:125]
	v_pk_add_f32 v[220:221], v[220:221], v[118:119]
	v_pk_add_f32 v[222:223], v[222:223], v[120:121]
	v_pk_mul_f32 v[180:181], v[34:35], s[74:75] op_sel_hi:[1,0]
	v_pk_mul_f32 v[182:183], v[36:37], s[74:75] op_sel_hi:[1,0]
	v_pk_mul_f32 v[184:185], v[38:39], s[74:75] op_sel_hi:[1,0]
	v_pk_mul_f32 v[186:187], v[40:41], s[74:75] op_sel_hi:[1,0]
	v_exp_f32_e32 v180, v180
	v_exp_f32_e32 v181, v181
	v_exp_f32_e32 v182, v182
	v_exp_f32_e32 v183, v183
	v_exp_f32_e32 v184, v184
	v_exp_f32_e32 v185, v185
	v_exp_f32_e32 v186, v186
	v_exp_f32_e32 v187, v187
	v_pk_fma_f32 v[188:189], v[114:115], s[24:25], v[236:237] op_sel_hi:[1,0,0]
	v_pk_fma_f32 v[190:191], v[116:117], s[24:25], v[236:237] op_sel_hi:[1,0,0]
	v_pk_fma_f32 v[192:193], v[106:107], s[24:25], v[236:237] op_sel_hi:[1,0,0]
	v_pk_fma_f32 v[194:195], v[108:109], s[24:25], v[236:237] op_sel_hi:[1,0,0]
	v_pk_add_f32 v[180:181], v[180:181], 1.0 op_sel_hi:[1,0]
	v_pk_add_f32 v[182:183], v[182:183], 1.0 op_sel_hi:[1,0]
	v_pk_add_f32 v[184:185], v[184:185], 1.0 op_sel_hi:[1,0]
	v_pk_add_f32 v[186:187], v[186:187], 1.0 op_sel_hi:[1,0]
	v_rcp_f32_e32 v180, v180
	v_rcp_f32_e32 v181, v181
	v_rcp_f32_e32 v182, v182
	v_rcp_f32_e32 v183, v183
	v_rcp_f32_e32 v184, v184
	v_rcp_f32_e32 v185, v185
	v_rcp_f32_e32 v186, v186
	v_rcp_f32_e32 v187, v187
;     __device__ __forceinline__ void operator()(AccMut acc, const Unit& u, int sw) const {
;     ...
;                 for (int n = 0; n < 2; ++n)
; #pragma unroll
;                     for (int jp = 0; jp < 2; ++jp) {
;                         const f32x2 z = (f32x2){acc[ai][1][m][n][2 * jp], acc[ai][1][m][n][2 * jp + 1]} * (-1.44269504f);
;                         f32x2 e; e.x = __builtin_amdgcn_exp2f(z.x); e.y = __builtin_amdgcn_exp2f(z.y); e = e + 1.0f;
;                         f32x2 ig; ig.x = __builtin_amdgcn_rcpf(e.x); ig.y = __builtin_amdgcn_rcpf(e.y);
;                         const f32x2 x2 = (f32x2){acc[ai][0][m][n][2 * jp], acc[ai][0][m][n][2 * jp + 1]} * 2.0f;
;                         f32x2 ser = x2 * (1.0f / 120.0f) + (1.0f / 24.0f); ser = ser * x2 + (1.0f / 6.0f); ser = ser * x2 + 0.5f; ser = ser * x2 + 1.0f; ser = ser * (-x2);
;                         f32x2 em = ser;
;                         if (__builtin_expect(__builtin_amdgcn_ballot_w64(x2.x <= -0.25f || x2.y <= -0.25f) != 0ull, 0)) {
;                             em.x = (x2.x > -0.25f) ? ser.x : (1.0f - fexp(x2.x)); em.y = (x2.y > -0.25f) ? ser.y : (1.0f - fexp(x2.y)); }
;                         const unsigned wv = xw[2 * n + jp];
;                         f32x2 sq; sq.x = __builtin_amdgcn_sqrtf(em.x); sq.y = __builtin_amdgcn_sqrtf(em.y);
;                         const f32x2 b2 = sq * ig * (f32x2){bf_lo(wv), bf_hi(wv)};
;                         bt[4 * n + 2 * jp] = b2.x; bt[4 * n + 2 * jp + 1] = b2.y; }
;                 u32x4 w; w.x = cvt_pk_bf16(bt[0], bt[1]); w.y = cvt_pk_bf16(bt[2], bt[3]); w.z = cvt_pk_bf16(bt[4], bt[5]); w.w = cvt_pk_bf16(bt[6], bt[7]);
;                 *(u32x4*)(BT + off) = w; }
; __device__ __forceinline__ void scan1_phase(const bf16_t* LA, const bf16_t* BT, int sw, View vw) {
;     ...
;             for (int i = 0; i < 8; ++i) {
;                 const float l0 = bf_lo(lw[i].x), l1 = bf_hi(lw[i].x), l2 = bf_lo(lw[i].y), l3 = bf_hi(lw[i].y);
;                 S[0] += l0; S[1] += l1; S[2] += l2; S[3] += l3;
;                 Hc[0] = fexp(l0) * Hc[0] + bf_lo(bw[i].x); Hc[1] = fexp(l1) * Hc[1] + bf_hi(bw[i].x); Hc[2] = fexp(l2) * Hc[2] + bf_lo(bw[i].y); Hc[3] = fexp(l3) * Hc[3] + bf_hi(bw[i].y); }
;         }
;         *(f32x4*)(CP + (size_t)bq * E + 4 * quad) = (f32x4){S[0], S[1], S[2], S[3]};
	v_pk_fma_f32 v[188:189], v[114:115], v[188:189], s[22:23] op_sel_hi:[1,1,0]
	v_pk_fma_f32 v[190:191], v[116:117], v[190:191], s[22:23] op_sel_hi:[1,1,0]
	v_pk_fma_f32 v[192:193], v[106:107], v[192:193], s[22:23] op_sel_hi:[1,1,0]
	v_pk_fma_f32 v[194:195], v[108:109], v[194:195], s[22:23] op_sel_hi:[1,1,0]
	v_pk_fma_f32 v[188:189], v[114:115], v[188:189], -2.0 op_sel_hi:[1,1,0]
	v_pk_fma_f32 v[190:191], v[116:117], v[190:191], -2.0 op_sel_hi:[1,1,0]
	v_pk_fma_f32 v[192:193], v[106:107], v[192:193], -2.0 op_sel_hi:[1,1,0]
	v_pk_fma_f32 v[194:195], v[108:109], v[194:195], -2.0 op_sel_hi:[1,1,0]
	v_pk_fma_f32 v[188:189], v[114:115], v[188:189], -2.0 op_sel_hi:[1,1,0]
	v_pk_fma_f32 v[190:191], v[116:117], v[190:191], -2.0 op_sel_hi:[1,1,0]
	v_pk_fma_f32 v[192:193], v[106:107], v[192:193], -2.0 op_sel_hi:[1,1,0]
	v_pk_fma_f32 v[194:195], v[108:109], v[194:195], -2.0 op_sel_hi:[1,1,0]
	v_pk_mul_f32 v[188:189], v[114:115], v[188:189]
	v_pk_mul_f32 v[190:191], v[116:117], v[190:191]
	v_pk_mul_f32 v[192:193], v[106:107], v[192:193]
	v_pk_mul_f32 v[194:195], v[108:109], v[194:195]
	v_pk_mul_f32 v[228:229], v[114:115], s[74:75] op_sel_hi:[1,0] neg_lo:[0,1] neg_hi:[0,1]
	v_pk_mul_f32 v[230:231], v[116:117], s[74:75] op_sel_hi:[1,0] neg_lo:[0,1] neg_hi:[0,1]
	v_pk_mul_f32 v[232:233], v[106:107], s[74:75] op_sel_hi:[1,0] neg_lo:[0,1] neg_hi:[0,1]
	v_pk_mul_f32 v[234:235], v[108:109], s[74:75] op_sel_hi:[1,0] neg_lo:[0,1] neg_hi:[0,1]
	v_sqrt_f32_e32 v188, v188
	v_sqrt_f32_e32 v189, v189
	v_sqrt_f32_e32 v190, v190
	v_sqrt_f32_e32 v191, v191
	v_sqrt_f32_e32 v192, v192
	v_sqrt_f32_e32 v193, v193
	v_sqrt_f32_e32 v194, v194
	v_sqrt_f32_e32 v195, v195
	v_exp_f32_e32 v228, v228
	v_exp_f32_e32 v229, v229
	v_exp_f32_e32 v230, v230
	v_exp_f32_e32 v231, v231
	v_exp_f32_e32 v232, v232
	v_exp_f32_e32 v233, v233
	v_exp_f32_e32 v234, v234
	v_exp_f32_e32 v235, v235
	s_waitcnt vmcnt(15)
	v_lshlrev_b32_e32 v196, 16, v148
	v_and_b32_e32 v197, 0xffff0000, v148
	v_lshlrev_b32_e32 v198, 16, v149
	v_and_b32_e32 v199, 0xffff0000, v149
	v_lshlrev_b32_e32 v200, 16, v150
	v_and_b32_e32 v201, 0xffff0000, v150
	v_lshlrev_b32_e32 v202, 16, v151
	v_and_b32_e32 v203, 0xffff0000, v151
	v_pk_mul_f32 v[188:189], v[188:189], v[180:181]
	v_pk_mul_f32 v[190:191], v[190:191], v[182:183]
	v_pk_mul_f32 v[192:193], v[192:193], v[184:185]
	v_pk_mul_f32 v[194:195], v[194:195], v[186:187]
	v_pk_mul_f32 v[188:189], v[188:189], v[196:197]
	v_pk_mul_f32 v[190:191], v[190:191], v[198:199]
	v_pk_mul_f32 v[192:193], v[192:193], v[200:201]
	v_pk_mul_f32 v[194:195], v[194:195], v[202:203]
	v_cvt_pk_bf16_f32 v212, v188, v189
	v_cvt_pk_bf16_f32 v213, v190, v191
	v_cvt_pk_bf16_f32 v214, v192, v193
	v_cvt_pk_bf16_f32 v215, v194, v195
	global_store_dwordx4 v173, v[212:215], s[10:11] nt
	v_pk_fma_f32 v[216:217], v[228:229], v[216:217], v[188:189]
	v_pk_fma_f32 v[218:219], v[230:231], v[218:219], v[190:191]
	v_pk_fma_f32 v[240:241], v[232:233], v[240:241], v[192:193]
	v_pk_fma_f32 v[242:243], v[234:235], v[242:243], v[194:195]
	v_pk_mul_f32 v[58:59], v[58:59], v[228:229]
	v_pk_mul_f32 v[60:61], v[60:61], v[230:231]
	v_pk_mul_f32 v[66:67], v[66:67], v[232:233]
	v_pk_mul_f32 v[68:69], v[68:69], v[234:235]
	v_pk_add_f32 v[204:205], v[204:205], v[114:115]
	v_pk_add_f32 v[206:207], v[206:207], v[116:117]
	v_pk_add_f32 v[220:221], v[220:221], v[106:107]
	v_pk_add_f32 v[222:223], v[222:223], v[108:109]
	v_fmac_f32_dpp v216, v216, v58 row_shr:1 row_mask:0xf bank_mask:0xf
	v_fmac_f32_dpp v217, v217, v59 row_shr:1 row_mask:0xf bank_mask:0xf
	v_fmac_f32_dpp v218, v218, v60 row_shr:1 row_mask:0xf bank_mask:0xf
	v_fmac_f32_dpp v219, v219, v61 row_shr:1 row_mask:0xf bank_mask:0xf
	v_fmac_f32_dpp v240, v240, v66 row_shr:1 row_mask:0xf bank_mask:0xf
	v_fmac_f32_dpp v241, v241, v67 row_shr:1 row_mask:0xf bank_mask:0xf
	v_fmac_f32_dpp v242, v242, v68 row_shr:1 row_mask:0xf bank_mask:0xf
	v_fmac_f32_dpp v243, v243, v69 row_shr:1 row_mask:0xf bank_mask:0xf
	v_mul_f32_dpp v58, v58, v58 row_shr:1 row_mask:0xf bank_mask:0xf
	v_mul_f32_dpp v59, v59, v59 row_shr:1 row_mask:0xf bank_mask:0xf
	v_mul_f32_dpp v60, v60, v60 row_shr:1 row_mask:0xf bank_mask:0xf
	v_mul_f32_dpp v61, v61, v61 row_shr:1 row_mask:0xf bank_mask:0xf
	v_mul_f32_dpp v66, v66, v66 row_shr:1 row_mask:0xf bank_mask:0xf
	v_mul_f32_dpp v67, v67, v67 row_shr:1 row_mask:0xf bank_mask:0xf
	v_mul_f32_dpp v68, v68, v68 row_shr:1 row_mask:0xf bank_mask:0xf
	v_mul_f32_dpp v69, v69, v69 row_shr:1 row_mask:0xf bank_mask:0xf
	v_add_f32_dpp v204, v204, v204 row_shr:1 row_mask:0xf bank_mask:0xf
	v_add_f32_dpp v205, v205, v205 row_shr:1 row_mask:0xf bank_mask:0xf
	v_add_f32_dpp v206, v206, v206 row_shr:1 row_mask:0xf bank_mask:0xf
	v_add_f32_dpp v207, v207, v207 row_shr:1 row_mask:0xf bank_mask:0xf
	v_add_f32_dpp v220, v220, v220 row_shr:1 row_mask:0xf bank_mask:0xf
	v_add_f32_dpp v221, v221, v221 row_shr:1 row_mask:0xf bank_mask:0xf
	v_add_f32_dpp v222, v222, v222 row_shr:1 row_mask:0xf bank_mask:0xf
	v_add_f32_dpp v223, v223, v223 row_shr:1 row_mask:0xf bank_mask:0xf
	v_fmac_f32_dpp v216, v216, v58 row_shr:2 row_mask:0xf bank_mask:0xf
	v_fmac_f32_dpp v217, v217, v59 row_shr:2 row_mask:0xf bank_mask:0xf
	v_fmac_f32_dpp v218, v218, v60 row_shr:2 row_mask:0xf bank_mask:0xf
	v_fmac_f32_dpp v219, v219, v61 row_shr:2 row_mask:0xf bank_mask:0xf
	v_fmac_f32_dpp v240, v240, v66 row_shr:2 row_mask:0xf bank_mask:0xf
	v_fmac_f32_dpp v241, v241, v67 row_shr:2 row_mask:0xf bank_mask:0xf
	v_fmac_f32_dpp v242, v242, v68 row_shr:2 row_mask:0xf bank_mask:0xf
	v_fmac_f32_dpp v243, v243, v69 row_shr:2 row_mask:0xf bank_mask:0xf
	v_mul_f32_dpp v58, v58, v58 row_shr:2 row_mask:0xf bank_mask:0xf
; __device__ __forceinline__ float bf_lo(unsigned w) { return __uint_as_float(w << 16); }
; __device__ __forceinline__ float bf_hi(unsigned w) { return __uint_as_float(w & 0xffff0000u); }
;     __device__ __forceinline__ void operator()(AccMut acc, const Unit& u, int sw) const {
;     ...
;                 for (int n = 0; n < 2; ++n)
; #pragma unroll
;                     for (int jp = 0; jp < 2; ++jp) {
;                         const f32x2 z = (f32x2){acc[ai][1][m][n][2 * jp], acc[ai][1][m][n][2 * jp + 1]} * (-1.44269504f);
;                         f32x2 e; e.x = __builtin_amdgcn_exp2f(z.x); e.y = __builtin_amdgcn_exp2f(z.y); e = e + 1.0f;
;                         f32x2 ig; ig.x = __builtin_amdgcn_rcpf(e.x); ig.y = __builtin_amdgcn_rcpf(e.y);
;                         const f32x2 x2 = (f32x2){acc[ai][0][m][n][2 * jp], acc[ai][0][m][n][2 * jp + 1]} * 2.0f;
;                         f32x2 ser = x2 * (1.0f / 120.0f) + (1.0f / 24.0f); ser = ser * x2 + (1.0f / 6.0f); ser = ser * x2 + 0.5f; ser = ser * x2 + 1.0f; ser = ser * (-x2);
;                         f32x2 em = ser;
;                         if (__builtin_expect(__builtin_amdgcn_ballot_w64(x2.x <= -0.25f || x2.y <= -0.25f) != 0ull, 0)) {
;                             em.x = (x2.x > -0.25f) ? ser.x : (1.0f - fexp(x2.x)); em.y = (x2.y > -0.25f) ? ser.y : (1.0f - fexp(x2.y)); }
;                         const unsigned wv = xw[2 * n + jp];
;                         f32x2 sq; sq.x = __builtin_amdgcn_sqrtf(em.x); sq.y = __builtin_amdgcn_sqrtf(em.y);
;                         const f32x2 b2 = sq * ig * (f32x2){bf_lo(wv), bf_hi(wv)};
;                         bt[4 * n + 2 * jp] = b2.x; bt[4 * n + 2 * jp + 1] = b2.y; }
; __device__ __forceinline__ void scan1_phase(const bf16_t* LA, const bf16_t* BT, int sw, View vw) {
;     ...
;             for (int i = 0; i < 8; ++i) {
;                 const float l0 = bf_lo(lw[i].x), l1 = bf_hi(lw[i].x), l2 = bf_lo(lw[i].y), l3 = bf_hi(lw[i].y);
;                 S[0] += l0; S[1] += l1; S[2] += l2; S[3] += l3;
;                 Hc[0] = fexp(l0) * Hc[0] + bf_lo(bw[i].x); Hc[1] = fexp(l1) * Hc[1] + bf_hi(bw[i].x); Hc[2] = fexp(l2) * Hc[2] + bf_lo(bw[i].y); Hc[3] = fexp(l3) * Hc[3] + bf_hi(bw[i].y); }
;         }
;         *(f32x4*)(CP + (size_t)bq * E + 4 * quad) = (f32x4){S[0], S[1], S[2], S[3]};
;         *(f32x4*)(CH + (size_t)bq * E + 4 * quad) = (f32x4){Hc[0], Hc[1], Hc[2], Hc[3]};
	v_mul_f32_dpp v59, v59, v59 row_shr:2 row_mask:0xf bank_mask:0xf
	v_mul_f32_dpp v60, v60, v60 row_shr:2 row_mask:0xf bank_mask:0xf
	v_mul_f32_dpp v61, v61, v61 row_shr:2 row_mask:0xf bank_mask:0xf
	v_mul_f32_dpp v66, v66, v66 row_shr:2 row_mask:0xf bank_mask:0xf
	v_mul_f32_dpp v67, v67, v67 row_shr:2 row_mask:0xf bank_mask:0xf
	v_mul_f32_dpp v68, v68, v68 row_shr:2 row_mask:0xf bank_mask:0xf
	v_mul_f32_dpp v69, v69, v69 row_shr:2 row_mask:0xf bank_mask:0xf
	v_add_f32_dpp v204, v204, v204 row_shr:2 row_mask:0xf bank_mask:0xf
	v_add_f32_dpp v205, v205, v205 row_shr:2 row_mask:0xf bank_mask:0xf
	v_add_f32_dpp v206, v206, v206 row_shr:2 row_mask:0xf bank_mask:0xf
	v_add_f32_dpp v207, v207, v207 row_shr:2 row_mask:0xf bank_mask:0xf
	v_add_f32_dpp v220, v220, v220 row_shr:2 row_mask:0xf bank_mask:0xf
	v_add_f32_dpp v221, v221, v221 row_shr:2 row_mask:0xf bank_mask:0xf
	v_add_f32_dpp v222, v222, v222 row_shr:2 row_mask:0xf bank_mask:0xf
	v_add_f32_dpp v223, v223, v223 row_shr:2 row_mask:0xf bank_mask:0xf
	v_fmac_f32_dpp v216, v216, v58 row_shr:4 row_mask:0xf bank_mask:0xf
	v_fmac_f32_dpp v217, v217, v59 row_shr:4 row_mask:0xf bank_mask:0xf
	v_fmac_f32_dpp v218, v218, v60 row_shr:4 row_mask:0xf bank_mask:0xf
	v_fmac_f32_dpp v219, v219, v61 row_shr:4 row_mask:0xf bank_mask:0xf
	v_fmac_f32_dpp v240, v240, v66 row_shr:4 row_mask:0xf bank_mask:0xf
	v_fmac_f32_dpp v241, v241, v67 row_shr:4 row_mask:0xf bank_mask:0xf
	v_fmac_f32_dpp v242, v242, v68 row_shr:4 row_mask:0xf bank_mask:0xf
	v_fmac_f32_dpp v243, v243, v69 row_shr:4 row_mask:0xf bank_mask:0xf
	v_mul_f32_dpp v58, v58, v58 row_shr:4 row_mask:0xf bank_mask:0xf
	v_mul_f32_dpp v59, v59, v59 row_shr:4 row_mask:0xf bank_mask:0xf
	v_mul_f32_dpp v60, v60, v60 row_shr:4 row_mask:0xf bank_mask:0xf
	v_mul_f32_dpp v61, v61, v61 row_shr:4 row_mask:0xf bank_mask:0xf
	v_mul_f32_dpp v66, v66, v66 row_shr:4 row_mask:0xf bank_mask:0xf
	v_mul_f32_dpp v67, v67, v67 row_shr:4 row_mask:0xf bank_mask:0xf
	v_mul_f32_dpp v68, v68, v68 row_shr:4 row_mask:0xf bank_mask:0xf
	v_mul_f32_dpp v69, v69, v69 row_shr:4 row_mask:0xf bank_mask:0xf
	v_add_f32_dpp v204, v204, v204 row_shr:4 row_mask:0xf bank_mask:0xf
	v_add_f32_dpp v205, v205, v205 row_shr:4 row_mask:0xf bank_mask:0xf
	v_add_f32_dpp v206, v206, v206 row_shr:4 row_mask:0xf bank_mask:0xf
	v_add_f32_dpp v207, v207, v207 row_shr:4 row_mask:0xf bank_mask:0xf
	v_add_f32_dpp v220, v220, v220 row_shr:4 row_mask:0xf bank_mask:0xf
	v_add_f32_dpp v221, v221, v221 row_shr:4 row_mask:0xf bank_mask:0xf
	v_add_f32_dpp v222, v222, v222 row_shr:4 row_mask:0xf bank_mask:0xf
	v_add_f32_dpp v223, v223, v223 row_shr:4 row_mask:0xf bank_mask:0xf
	v_fmac_f32_dpp v216, v216, v58 row_shr:8 row_mask:0xf bank_mask:0xf
	v_fmac_f32_dpp v217, v217, v59 row_shr:8 row_mask:0xf bank_mask:0xf
	v_fmac_f32_dpp v218, v218, v60 row_shr:8 row_mask:0xf bank_mask:0xf
	v_fmac_f32_dpp v219, v219, v61 row_shr:8 row_mask:0xf bank_mask:0xf
	v_fmac_f32_dpp v240, v240, v66 row_shr:8 row_mask:0xf bank_mask:0xf
	v_fmac_f32_dpp v241, v241, v67 row_shr:8 row_mask:0xf bank_mask:0xf
	v_fmac_f32_dpp v242, v242, v68 row_shr:8 row_mask:0xf bank_mask:0xf
	v_fmac_f32_dpp v243, v243, v69 row_shr:8 row_mask:0xf bank_mask:0xf
	v_add_f32_dpp v204, v204, v204 row_shr:8 row_mask:0xf bank_mask:0xf
	v_add_f32_dpp v205, v205, v205 row_shr:8 row_mask:0xf bank_mask:0xf
	v_add_f32_dpp v206, v206, v206 row_shr:8 row_mask:0xf bank_mask:0xf
	v_add_f32_dpp v207, v207, v207 row_shr:8 row_mask:0xf bank_mask:0xf
	v_add_f32_dpp v220, v220, v220 row_shr:8 row_mask:0xf bank_mask:0xf
	v_add_f32_dpp v221, v221, v221 row_shr:8 row_mask:0xf bank_mask:0xf
	v_add_f32_dpp v222, v222, v222 row_shr:8 row_mask:0xf bank_mask:0xf
	v_add_f32_dpp v223, v223, v223 row_shr:8 row_mask:0xf bank_mask:0xf
	v_mbcnt_lo_u32_b32 v180, -1, 0
	v_mbcnt_hi_u32_b32 v180, -1, v180
	v_and_b32_e32 v180, 15, v180
	v_cmp_eq_u32_e32 vcc, 15, v180
	v_add_u32_e32 v181, 0x0, v239
	v_add_u32_e32 v182, 0x400000, v239
	s_mov_b64 exec, vcc
	global_store_dwordx4 v181, v[204:207], s[26:27]
	global_store_dwordx4 v181, v[220:223], s[26:27] offset:16
	global_store_dwordx4 v182, v[216:219], s[26:27]
	global_store_dwordx4 v182, v[240:243], s[26:27] offset:16
	s_mov_b64 exec, -1
	v_pk_mul_f32 v[180:181], v[26:27], s[74:75] op_sel_hi:[1,0]
	v_pk_mul_f32 v[182:183], v[28:29], s[74:75] op_sel_hi:[1,0]
	v_pk_mul_f32 v[184:185], v[30:31], s[74:75] op_sel_hi:[1,0]
	v_pk_mul_f32 v[186:187], v[32:33], s[74:75] op_sel_hi:[1,0]
	v_exp_f32_e32 v180, v180
	v_exp_f32_e32 v181, v181
	v_exp_f32_e32 v182, v182
	v_exp_f32_e32 v183, v183
	v_exp_f32_e32 v184, v184
	v_exp_f32_e32 v185, v185
	v_exp_f32_e32 v186, v186
	v_exp_f32_e32 v187, v187
	v_pk_fma_f32 v[188:189], v[110:111], s[24:25], v[236:237] op_sel_hi:[1,0,0]
	v_pk_fma_f32 v[190:191], v[112:113], s[24:25], v[236:237] op_sel_hi:[1,0,0]
	v_pk_fma_f32 v[192:193], v[102:103], s[24:25], v[236:237] op_sel_hi:[1,0,0]
	v_pk_fma_f32 v[194:195], v[104:105], s[24:25], v[236:237] op_sel_hi:[1,0,0]
	v_pk_add_f32 v[180:181], v[180:181], 1.0 op_sel_hi:[1,0]
	v_pk_add_f32 v[182:183], v[182:183], 1.0 op_sel_hi:[1,0]
	v_pk_add_f32 v[184:185], v[184:185], 1.0 op_sel_hi:[1,0]
	v_pk_add_f32 v[186:187], v[186:187], 1.0 op_sel_hi:[1,0]
	v_rcp_f32_e32 v180, v180
	v_rcp_f32_e32 v181, v181
	v_rcp_f32_e32 v182, v182
	v_rcp_f32_e32 v183, v183
	v_rcp_f32_e32 v184, v184
	v_rcp_f32_e32 v185, v185
	v_rcp_f32_e32 v186, v186
	v_rcp_f32_e32 v187, v187
	v_pk_fma_f32 v[188:189], v[110:111], v[188:189], s[22:23] op_sel_hi:[1,1,0]
	v_pk_fma_f32 v[190:191], v[112:113], v[190:191], s[22:23] op_sel_hi:[1,1,0]
	v_pk_fma_f32 v[192:193], v[102:103], v[192:193], s[22:23] op_sel_hi:[1,1,0]
; __device__ __forceinline__ unsigned cvt_pk_bf16(float lo, float hi) { unsigned r; asm volatile("v_cvt_pk_bf16_f32 %0, %1, %2" : "=v"(r) : "v"(lo), "v"(hi)); return r; }
; __device__ __forceinline__ float bf_lo(unsigned w) { return __uint_as_float(w << 16); }
; __device__ __forceinline__ float bf_hi(unsigned w) { return __uint_as_float(w & 0xffff0000u); }
; __device__ __forceinline__ float fexp(float x) { return __builtin_amdgcn_exp2f(1.44269504f * x); }
;     __device__ __forceinline__ void operator()(AccMut acc, const Unit& u, int sw) const {
;     ...
;                 for (int n = 0; n < 2; ++n)
; #pragma unroll
;                     for (int jp = 0; jp < 2; ++jp) {
;                         const f32x2 z = (f32x2){acc[ai][1][m][n][2 * jp], acc[ai][1][m][n][2 * jp + 1]} * (-1.44269504f);
;                         f32x2 e; e.x = __builtin_amdgcn_exp2f(z.x); e.y = __builtin_amdgcn_exp2f(z.y); e = e + 1.0f;
;                         f32x2 ig; ig.x = __builtin_amdgcn_rcpf(e.x); ig.y = __builtin_amdgcn_rcpf(e.y);
;                         const f32x2 x2 = (f32x2){acc[ai][0][m][n][2 * jp], acc[ai][0][m][n][2 * jp + 1]} * 2.0f;
;                         f32x2 ser = x2 * (1.0f / 120.0f) + (1.0f / 24.0f); ser = ser * x2 + (1.0f / 6.0f); ser = ser * x2 + 0.5f; ser = ser * x2 + 1.0f; ser = ser * (-x2);
;                         f32x2 em = ser;
;                         if (__builtin_expect(__builtin_amdgcn_ballot_w64(x2.x <= -0.25f || x2.y <= -0.25f) != 0ull, 0)) {
;                             em.x = (x2.x > -0.25f) ? ser.x : (1.0f - fexp(x2.x)); em.y = (x2.y > -0.25f) ? ser.y : (1.0f - fexp(x2.y)); }
;                         const unsigned wv = xw[2 * n + jp];
;                         f32x2 sq; sq.x = __builtin_amdgcn_sqrtf(em.x); sq.y = __builtin_amdgcn_sqrtf(em.y);
;                         const f32x2 b2 = sq * ig * (f32x2){bf_lo(wv), bf_hi(wv)};
;                         bt[4 * n + 2 * jp] = b2.x; bt[4 * n + 2 * jp + 1] = b2.y; }
;                 u32x4 w; w.x = cvt_pk_bf16(bt[0], bt[1]); w.y = cvt_pk_bf16(bt[2], bt[3]); w.z = cvt_pk_bf16(bt[4], bt[5]); w.w = cvt_pk_bf16(bt[6], bt[7]);
;                 *(u32x4*)(BT + off) = w; }
	v_pk_fma_f32 v[194:195], v[104:105], v[194:195], s[22:23] op_sel_hi:[1,1,0]
	v_pk_fma_f32 v[188:189], v[110:111], v[188:189], -2.0 op_sel_hi:[1,1,0]
	v_pk_fma_f32 v[190:191], v[112:113], v[190:191], -2.0 op_sel_hi:[1,1,0]
	v_pk_fma_f32 v[192:193], v[102:103], v[192:193], -2.0 op_sel_hi:[1,1,0]
	v_pk_fma_f32 v[194:195], v[104:105], v[194:195], -2.0 op_sel_hi:[1,1,0]
	v_pk_fma_f32 v[188:189], v[110:111], v[188:189], -2.0 op_sel_hi:[1,1,0]
	v_pk_fma_f32 v[190:191], v[112:113], v[190:191], -2.0 op_sel_hi:[1,1,0]
	v_pk_fma_f32 v[192:193], v[102:103], v[192:193], -2.0 op_sel_hi:[1,1,0]
	v_pk_fma_f32 v[194:195], v[104:105], v[194:195], -2.0 op_sel_hi:[1,1,0]
	v_pk_mul_f32 v[188:189], v[110:111], v[188:189]
	v_pk_mul_f32 v[190:191], v[112:113], v[190:191]
	v_pk_mul_f32 v[192:193], v[102:103], v[192:193]
	v_pk_mul_f32 v[194:195], v[104:105], v[194:195]
	v_pk_mul_f32 v[228:229], v[110:111], s[74:75] op_sel_hi:[1,0] neg_lo:[0,1] neg_hi:[0,1]
	v_pk_mul_f32 v[230:231], v[112:113], s[74:75] op_sel_hi:[1,0] neg_lo:[0,1] neg_hi:[0,1]
	v_pk_mul_f32 v[232:233], v[102:103], s[74:75] op_sel_hi:[1,0] neg_lo:[0,1] neg_hi:[0,1]
	v_pk_mul_f32 v[234:235], v[104:105], s[74:75] op_sel_hi:[1,0] neg_lo:[0,1] neg_hi:[0,1]
	v_sqrt_f32_e32 v188, v188
	v_sqrt_f32_e32 v189, v189
	v_sqrt_f32_e32 v190, v190
	v_sqrt_f32_e32 v191, v191
	v_sqrt_f32_e32 v192, v192
	v_sqrt_f32_e32 v193, v193
	v_sqrt_f32_e32 v194, v194
	v_sqrt_f32_e32 v195, v195
	v_exp_f32_e32 v26, v228
	v_exp_f32_e32 v27, v229
	v_exp_f32_e32 v28, v230
	v_exp_f32_e32 v29, v231
	v_exp_f32_e32 v30, v232
	v_exp_f32_e32 v31, v233
	v_exp_f32_e32 v32, v234
	v_exp_f32_e32 v33, v235
	s_waitcnt vmcnt(19)
	v_lshlrev_b32_e32 v196, 16, v152
	v_and_b32_e32 v197, 0xffff0000, v152
	v_lshlrev_b32_e32 v198, 16, v153
	v_and_b32_e32 v199, 0xffff0000, v153
	v_lshlrev_b32_e32 v200, 16, v154
	v_and_b32_e32 v201, 0xffff0000, v154
	v_lshlrev_b32_e32 v202, 16, v155
	v_and_b32_e32 v203, 0xffff0000, v155
	v_pk_mul_f32 v[188:189], v[188:189], v[180:181]
	v_pk_mul_f32 v[190:191], v[190:191], v[182:183]
	v_pk_mul_f32 v[192:193], v[192:193], v[184:185]
	v_pk_mul_f32 v[194:195], v[194:195], v[186:187]
	v_pk_mul_f32 v[216:217], v[188:189], v[196:197]
	v_pk_mul_f32 v[218:219], v[190:191], v[198:199]
	v_pk_mul_f32 v[240:241], v[192:193], v[200:201]
	v_pk_mul_f32 v[242:243], v[194:195], v[202:203]
	v_cvt_pk_bf16_f32 v208, v216, v217
	v_cvt_pk_bf16_f32 v209, v218, v219
	v_cvt_pk_bf16_f32 v210, v240, v241
	v_cvt_pk_bf16_f32 v211, v242, v243
	global_store_dwordx4 v176, v[208:211], s[10:11] nt
	v_pk_mul_f32 v[180:181], v[18:19], s[74:75] op_sel_hi:[1,0]
	v_pk_mul_f32 v[182:183], v[20:21], s[74:75] op_sel_hi:[1,0]
	v_pk_mul_f32 v[184:185], v[22:23], s[74:75] op_sel_hi:[1,0]
	v_pk_mul_f32 v[186:187], v[24:25], s[74:75] op_sel_hi:[1,0]
	v_exp_f32_e32 v180, v180
	v_exp_f32_e32 v181, v181
	v_exp_f32_e32 v182, v182
	v_exp_f32_e32 v183, v183
	v_exp_f32_e32 v184, v184
	v_exp_f32_e32 v185, v185
	v_exp_f32_e32 v186, v186
	v_exp_f32_e32 v187, v187
	v_pk_fma_f32 v[188:189], v[98:99], s[24:25], v[236:237] op_sel_hi:[1,0,0]
	v_pk_fma_f32 v[190:191], v[100:101], s[24:25], v[236:237] op_sel_hi:[1,0,0]
	v_pk_fma_f32 v[192:193], v[94:95], s[24:25], v[236:237] op_sel_hi:[1,0,0]
	v_pk_fma_f32 v[194:195], v[96:97], s[24:25], v[236:237] op_sel_hi:[1,0,0]
	v_pk_add_f32 v[180:181], v[180:181], 1.0 op_sel_hi:[1,0]
	v_pk_add_f32 v[182:183], v[182:183], 1.0 op_sel_hi:[1,0]
	v_pk_add_f32 v[184:185], v[184:185], 1.0 op_sel_hi:[1,0]
	v_pk_add_f32 v[186:187], v[186:187], 1.0 op_sel_hi:[1,0]
	v_rcp_f32_e32 v180, v180
	v_rcp_f32_e32 v181, v181
	v_rcp_f32_e32 v182, v182
	v_rcp_f32_e32 v183, v183
	v_rcp_f32_e32 v184, v184
	v_rcp_f32_e32 v185, v185
	v_rcp_f32_e32 v186, v186
	v_rcp_f32_e32 v187, v187
	v_pk_fma_f32 v[188:189], v[98:99], v[188:189], s[22:23] op_sel_hi:[1,1,0]
	v_pk_fma_f32 v[190:191], v[100:101], v[190:191], s[22:23] op_sel_hi:[1,1,0]
	v_pk_fma_f32 v[192:193], v[94:95], v[192:193], s[22:23] op_sel_hi:[1,1,0]
	v_pk_fma_f32 v[194:195], v[96:97], v[194:195], s[22:23] op_sel_hi:[1,1,0]
	v_pk_fma_f32 v[188:189], v[98:99], v[188:189], -2.0 op_sel_hi:[1,1,0]
	v_pk_fma_f32 v[190:191], v[100:101], v[190:191], -2.0 op_sel_hi:[1,1,0]
	v_pk_fma_f32 v[192:193], v[94:95], v[192:193], -2.0 op_sel_hi:[1,1,0]
	v_pk_fma_f32 v[194:195], v[96:97], v[194:195], -2.0 op_sel_hi:[1,1,0]
	v_pk_fma_f32 v[188:189], v[98:99], v[188:189], -2.0 op_sel_hi:[1,1,0]
	v_pk_fma_f32 v[190:191], v[100:101], v[190:191], -2.0 op_sel_hi:[1,1,0]
	v_pk_fma_f32 v[192:193], v[94:95], v[192:193], -2.0 op_sel_hi:[1,1,0]
	v_pk_fma_f32 v[194:195], v[96:97], v[194:195], -2.0 op_sel_hi:[1,1,0]
	v_pk_mul_f32 v[188:189], v[98:99], v[188:189]
	v_pk_mul_f32 v[190:191], v[100:101], v[190:191]
	v_pk_mul_f32 v[192:193], v[94:95], v[192:193]
	v_pk_mul_f32 v[194:195], v[96:97], v[194:195]
	v_pk_mul_f32 v[228:229], v[98:99], s[74:75] op_sel_hi:[1,0] neg_lo:[0,1] neg_hi:[0,1]
	v_pk_mul_f32 v[230:231], v[100:101], s[74:75] op_sel_hi:[1,0] neg_lo:[0,1] neg_hi:[0,1]
	v_pk_mul_f32 v[232:233], v[94:95], s[74:75] op_sel_hi:[1,0] neg_lo:[0,1] neg_hi:[0,1]
	v_pk_mul_f32 v[234:235], v[96:97], s[74:75] op_sel_hi:[1,0] neg_lo:[0,1] neg_hi:[0,1]
	v_sqrt_f32_e32 v188, v188
	v_sqrt_f32_e32 v189, v189
	v_sqrt_f32_e32 v190, v190
	v_sqrt_f32_e32 v191, v191
	v_sqrt_f32_e32 v192, v192
	v_sqrt_f32_e32 v193, v193
	v_sqrt_f32_e32 v194, v194
	v_sqrt_f32_e32 v195, v195
	v_exp_f32_e32 v228, v228
	v_exp_f32_e32 v229, v229
	v_exp_f32_e32 v230, v230
	v_exp_f32_e32 v231, v231
	v_exp_f32_e32 v232, v232
	v_exp_f32_e32 v233, v233
	v_exp_f32_e32 v234, v234
	v_exp_f32_e32 v235, v235
	s_waitcnt vmcnt(19)
; __device__ __forceinline__ unsigned cvt_pk_bf16(float lo, float hi) { unsigned r; asm volatile("v_cvt_pk_bf16_f32 %0, %1, %2" : "=v"(r) : "v"(lo), "v"(hi)); return r; }
;     __device__ __forceinline__ void operator()(AccMut acc, const Unit& u, int sw) const {
;     ...
;                 for (int n = 0; n < 2; ++n)
; #pragma unroll
;                     for (int jp = 0; jp < 2; ++jp) {
;                         const f32x2 z = (f32x2){acc[ai][1][m][n][2 * jp], acc[ai][1][m][n][2 * jp + 1]} * (-1.44269504f);
;                         f32x2 e; e.x = __builtin_amdgcn_exp2f(z.x); e.y = __builtin_amdgcn_exp2f(z.y); e = e + 1.0f;
;                         f32x2 ig; ig.x = __builtin_amdgcn_rcpf(e.x); ig.y = __builtin_amdgcn_rcpf(e.y);
;                         const f32x2 x2 = (f32x2){acc[ai][0][m][n][2 * jp], acc[ai][0][m][n][2 * jp + 1]} * 2.0f;
;                         f32x2 ser = x2 * (1.0f / 120.0f) + (1.0f / 24.0f); ser = ser * x2 + (1.0f / 6.0f); ser = ser * x2 + 0.5f; ser = ser * x2 + 1.0f; ser = ser * (-x2);
;                         f32x2 em = ser;
;                         if (__builtin_expect(__builtin_amdgcn_ballot_w64(x2.x <= -0.25f || x2.y <= -0.25f) != 0ull, 0)) {
;                             em.x = (x2.x > -0.25f) ? ser.x : (1.0f - fexp(x2.x)); em.y = (x2.y > -0.25f) ? ser.y : (1.0f - fexp(x2.y)); }
;                         const unsigned wv = xw[2 * n + jp];
;                         f32x2 sq; sq.x = __builtin_amdgcn_sqrtf(em.x); sq.y = __builtin_amdgcn_sqrtf(em.y);
;                         const f32x2 b2 = sq * ig * (f32x2){bf_lo(wv), bf_hi(wv)};
;                         bt[4 * n + 2 * jp] = b2.x; bt[4 * n + 2 * jp + 1] = b2.y; }
;                 u32x4 w; w.x = cvt_pk_bf16(bt[0], bt[1]); w.y = cvt_pk_bf16(bt[2], bt[3]); w.z = cvt_pk_bf16(bt[4], bt[5]); w.w = cvt_pk_bf16(bt[6], bt[7]);
;                 *(u32x4*)(BT + off) = w; }
; __device__ __forceinline__ void scan1_phase(const bf16_t* LA, const bf16_t* BT, int sw, View vw) {
;     ...
;             for (int i = 0; i < 8; ++i) {
;                 const float l0 = bf_lo(lw[i].x), l1 = bf_hi(lw[i].x), l2 = bf_lo(lw[i].y), l3 = bf_hi(lw[i].y);
;                 S[0] += l0; S[1] += l1; S[2] += l2; S[3] += l3;
;                 Hc[0] = fexp(l0) * Hc[0] + bf_lo(bw[i].x); Hc[1] = fexp(l1) * Hc[1] + bf_hi(bw[i].x); Hc[2] = fexp(l2) * Hc[2] + bf_lo(bw[i].y); Hc[3] = fexp(l3) * Hc[3] + bf_hi(bw[i].y); }
	v_lshlrev_b32_e32 v196, 16, v156
	v_and_b32_e32 v197, 0xffff0000, v156
	v_lshlrev_b32_e32 v198, 16, v157
	v_and_b32_e32 v199, 0xffff0000, v157
	v_lshlrev_b32_e32 v200, 16, v158
	v_and_b32_e32 v201, 0xffff0000, v158
	v_lshlrev_b32_e32 v202, 16, v159
	v_and_b32_e32 v203, 0xffff0000, v159
	v_pk_mul_f32 v[188:189], v[188:189], v[180:181]
	v_pk_mul_f32 v[190:191], v[190:191], v[182:183]
	v_pk_mul_f32 v[192:193], v[192:193], v[184:185]
	v_pk_mul_f32 v[194:195], v[194:195], v[186:187]
	v_pk_mul_f32 v[188:189], v[188:189], v[196:197]
	v_pk_mul_f32 v[190:191], v[190:191], v[198:199]
	v_pk_mul_f32 v[192:193], v[192:193], v[200:201]
	v_pk_mul_f32 v[194:195], v[194:195], v[202:203]
	v_cvt_pk_bf16_f32 v212, v188, v189
	v_cvt_pk_bf16_f32 v213, v190, v191
	v_cvt_pk_bf16_f32 v214, v192, v193
	v_cvt_pk_bf16_f32 v215, v194, v195
	global_store_dwordx4 v177, v[212:215], s[10:11] nt
	v_pk_fma_f32 v[216:217], v[228:229], v[216:217], v[188:189]
	v_pk_fma_f32 v[218:219], v[230:231], v[218:219], v[190:191]
	v_pk_fma_f32 v[240:241], v[232:233], v[240:241], v[192:193]
	v_pk_fma_f32 v[242:243], v[234:235], v[242:243], v[194:195]
	v_pk_mul_f32 v[26:27], v[26:27], v[228:229]
	v_pk_mul_f32 v[28:29], v[28:29], v[230:231]
	v_pk_mul_f32 v[30:31], v[30:31], v[232:233]
	v_pk_mul_f32 v[32:33], v[32:33], v[234:235]
	v_pk_add_f32 v[110:111], v[110:111], v[98:99]
	v_pk_add_f32 v[112:113], v[112:113], v[100:101]
	v_pk_add_f32 v[102:103], v[102:103], v[94:95]
	v_pk_add_f32 v[104:105], v[104:105], v[96:97]
	v_pk_mul_f32 v[180:181], v[10:11], s[74:75] op_sel_hi:[1,0]
	v_pk_mul_f32 v[182:183], v[12:13], s[74:75] op_sel_hi:[1,0]
	v_pk_mul_f32 v[184:185], v[14:15], s[74:75] op_sel_hi:[1,0]
	v_pk_mul_f32 v[186:187], v[16:17], s[74:75] op_sel_hi:[1,0]
	v_exp_f32_e32 v180, v180
	v_exp_f32_e32 v181, v181
	v_exp_f32_e32 v182, v182
	v_exp_f32_e32 v183, v183
	v_exp_f32_e32 v184, v184
	v_exp_f32_e32 v185, v185
	v_exp_f32_e32 v186, v186
	v_exp_f32_e32 v187, v187
	v_pk_fma_f32 v[188:189], v[90:91], s[24:25], v[236:237] op_sel_hi:[1,0,0]
	v_pk_fma_f32 v[190:191], v[92:93], s[24:25], v[236:237] op_sel_hi:[1,0,0]
	v_pk_fma_f32 v[192:193], v[86:87], s[24:25], v[236:237] op_sel_hi:[1,0,0]
	v_pk_fma_f32 v[194:195], v[88:89], s[24:25], v[236:237] op_sel_hi:[1,0,0]
	v_pk_add_f32 v[180:181], v[180:181], 1.0 op_sel_hi:[1,0]
	v_pk_add_f32 v[182:183], v[182:183], 1.0 op_sel_hi:[1,0]
	v_pk_add_f32 v[184:185], v[184:185], 1.0 op_sel_hi:[1,0]
	v_pk_add_f32 v[186:187], v[186:187], 1.0 op_sel_hi:[1,0]
	v_rcp_f32_e32 v180, v180
	v_rcp_f32_e32 v181, v181
	v_rcp_f32_e32 v182, v182
	v_rcp_f32_e32 v183, v183
	v_rcp_f32_e32 v184, v184
	v_rcp_f32_e32 v185, v185
	v_rcp_f32_e32 v186, v186
	v_rcp_f32_e32 v187, v187
	v_pk_fma_f32 v[188:189], v[90:91], v[188:189], s[22:23] op_sel_hi:[1,1,0]
	v_pk_fma_f32 v[190:191], v[92:93], v[190:191], s[22:23] op_sel_hi:[1,1,0]
	v_pk_fma_f32 v[192:193], v[86:87], v[192:193], s[22:23] op_sel_hi:[1,1,0]
	v_pk_fma_f32 v[194:195], v[88:89], v[194:195], s[22:23] op_sel_hi:[1,1,0]
	v_pk_fma_f32 v[188:189], v[90:91], v[188:189], -2.0 op_sel_hi:[1,1,0]
	v_pk_fma_f32 v[190:191], v[92:93], v[190:191], -2.0 op_sel_hi:[1,1,0]
	v_pk_fma_f32 v[192:193], v[86:87], v[192:193], -2.0 op_sel_hi:[1,1,0]
	v_pk_fma_f32 v[194:195], v[88:89], v[194:195], -2.0 op_sel_hi:[1,1,0]
	v_pk_fma_f32 v[188:189], v[90:91], v[188:189], -2.0 op_sel_hi:[1,1,0]
	v_pk_fma_f32 v[190:191], v[92:93], v[190:191], -2.0 op_sel_hi:[1,1,0]
	v_pk_fma_f32 v[192:193], v[86:87], v[192:193], -2.0 op_sel_hi:[1,1,0]
	v_pk_fma_f32 v[194:195], v[88:89], v[194:195], -2.0 op_sel_hi:[1,1,0]
	v_pk_mul_f32 v[188:189], v[90:91], v[188:189]
	v_pk_mul_f32 v[190:191], v[92:93], v[190:191]
	v_pk_mul_f32 v[192:193], v[86:87], v[192:193]
	v_pk_mul_f32 v[194:195], v[88:89], v[194:195]
	v_pk_mul_f32 v[228:229], v[90:91], s[74:75] op_sel_hi:[1,0] neg_lo:[0,1] neg_hi:[0,1]
	v_pk_mul_f32 v[230:231], v[92:93], s[74:75] op_sel_hi:[1,0] neg_lo:[0,1] neg_hi:[0,1]
	v_pk_mul_f32 v[232:233], v[86:87], s[74:75] op_sel_hi:[1,0] neg_lo:[0,1] neg_hi:[0,1]
	v_pk_mul_f32 v[234:235], v[88:89], s[74:75] op_sel_hi:[1,0] neg_lo:[0,1] neg_hi:[0,1]
	v_sqrt_f32_e32 v188, v188
	v_sqrt_f32_e32 v189, v189
	v_sqrt_f32_e32 v190, v190
	v_sqrt_f32_e32 v191, v191
	v_sqrt_f32_e32 v192, v192
	v_sqrt_f32_e32 v193, v193
	v_sqrt_f32_e32 v194, v194
	v_sqrt_f32_e32 v195, v195
	v_exp_f32_e32 v228, v228
	v_exp_f32_e32 v229, v229
	v_exp_f32_e32 v230, v230
	v_exp_f32_e32 v231, v231
	v_exp_f32_e32 v232, v232
	v_exp_f32_e32 v233, v233
	v_exp_f32_e32 v234, v234
	v_exp_f32_e32 v235, v235
	s_waitcnt vmcnt(19)
; __device__ __forceinline__ unsigned cvt_pk_bf16(float lo, float hi) { unsigned r; asm volatile("v_cvt_pk_bf16_f32 %0, %1, %2" : "=v"(r) : "v"(lo), "v"(hi)); return r; }
;     __device__ __forceinline__ void operator()(AccMut acc, const Unit& u, int sw) const {
;     ...
;                 for (int n = 0; n < 2; ++n)
; #pragma unroll
;                     for (int jp = 0; jp < 2; ++jp) {
;                         const f32x2 z = (f32x2){acc[ai][1][m][n][2 * jp], acc[ai][1][m][n][2 * jp + 1]} * (-1.44269504f);
;                         f32x2 e; e.x = __builtin_amdgcn_exp2f(z.x); e.y = __builtin_amdgcn_exp2f(z.y); e = e + 1.0f;
;                         f32x2 ig; ig.x = __builtin_amdgcn_rcpf(e.x); ig.y = __builtin_amdgcn_rcpf(e.y);
;                         const f32x2 x2 = (f32x2){acc[ai][0][m][n][2 * jp], acc[ai][0][m][n][2 * jp + 1]} * 2.0f;
;                         f32x2 ser = x2 * (1.0f / 120.0f) + (1.0f / 24.0f); ser = ser * x2 + (1.0f / 6.0f); ser = ser * x2 + 0.5f; ser = ser * x2 + 1.0f; ser = ser * (-x2);
;                         f32x2 em = ser;
;                         if (__builtin_expect(__builtin_amdgcn_ballot_w64(x2.x <= -0.25f || x2.y <= -0.25f) != 0ull, 0)) {
;                             em.x = (x2.x > -0.25f) ? ser.x : (1.0f - fexp(x2.x)); em.y = (x2.y > -0.25f) ? ser.y : (1.0f - fexp(x2.y)); }
;                         const unsigned wv = xw[2 * n + jp];
;                         f32x2 sq; sq.x = __builtin_amdgcn_sqrtf(em.x); sq.y = __builtin_amdgcn_sqrtf(em.y);
;                         const f32x2 b2 = sq * ig * (f32x2){bf_lo(wv), bf_hi(wv)};
;                         bt[4 * n + 2 * jp] = b2.x; bt[4 * n + 2 * jp + 1] = b2.y; }
;                 u32x4 w; w.x = cvt_pk_bf16(bt[0], bt[1]); w.y = cvt_pk_bf16(bt[2], bt[3]); w.z = cvt_pk_bf16(bt[4], bt[5]); w.w = cvt_pk_bf16(bt[6], bt[7]);
;                 *(u32x4*)(BT + off) = w; }
; __device__ __forceinline__ void scan1_phase(const bf16_t* LA, const bf16_t* BT, int sw, View vw) {
;     ...
;             for (int i = 0; i < 8; ++i) {
;                 const float l0 = bf_lo(lw[i].x), l1 = bf_hi(lw[i].x), l2 = bf_lo(lw[i].y), l3 = bf_hi(lw[i].y);
;                 S[0] += l0; S[1] += l1; S[2] += l2; S[3] += l3;
;                 Hc[0] = fexp(l0) * Hc[0] + bf_lo(bw[i].x); Hc[1] = fexp(l1) * Hc[1] + bf_hi(bw[i].x); Hc[2] = fexp(l2) * Hc[2] + bf_lo(bw[i].y); Hc[3] = fexp(l3) * Hc[3] + bf_hi(bw[i].y); }
	v_lshlrev_b32_e32 v196, 16, v160
	v_and_b32_e32 v197, 0xffff0000, v160
	v_lshlrev_b32_e32 v198, 16, v161
	v_and_b32_e32 v199, 0xffff0000, v161
	v_lshlrev_b32_e32 v200, 16, v162
	v_and_b32_e32 v201, 0xffff0000, v162
	v_lshlrev_b32_e32 v202, 16, v163
	v_and_b32_e32 v203, 0xffff0000, v163
	v_pk_mul_f32 v[188:189], v[188:189], v[180:181]
	v_pk_mul_f32 v[190:191], v[190:191], v[182:183]
	v_pk_mul_f32 v[192:193], v[192:193], v[184:185]
	v_pk_mul_f32 v[194:195], v[194:195], v[186:187]
	v_pk_mul_f32 v[188:189], v[188:189], v[196:197]
	v_pk_mul_f32 v[190:191], v[190:191], v[198:199]
	v_pk_mul_f32 v[192:193], v[192:193], v[200:201]
	v_pk_mul_f32 v[194:195], v[194:195], v[202:203]
	v_cvt_pk_bf16_f32 v208, v188, v189
	v_cvt_pk_bf16_f32 v209, v190, v191
	v_cvt_pk_bf16_f32 v210, v192, v193
	v_cvt_pk_bf16_f32 v211, v194, v195
	global_store_dwordx4 v178, v[208:211], s[10:11] nt
	v_pk_fma_f32 v[216:217], v[228:229], v[216:217], v[188:189]
	v_pk_fma_f32 v[218:219], v[230:231], v[218:219], v[190:191]
	v_pk_fma_f32 v[240:241], v[232:233], v[240:241], v[192:193]
	v_pk_fma_f32 v[242:243], v[234:235], v[242:243], v[194:195]
	v_pk_mul_f32 v[26:27], v[26:27], v[228:229]
	v_pk_mul_f32 v[28:29], v[28:29], v[230:231]
	v_pk_mul_f32 v[30:31], v[30:31], v[232:233]
	v_pk_mul_f32 v[32:33], v[32:33], v[234:235]
	v_pk_add_f32 v[110:111], v[110:111], v[90:91]
	v_pk_add_f32 v[112:113], v[112:113], v[92:93]
	v_pk_add_f32 v[102:103], v[102:103], v[86:87]
	v_pk_add_f32 v[104:105], v[104:105], v[88:89]
	v_pk_mul_f32 v[180:181], v[2:3], s[74:75] op_sel_hi:[1,0]
	v_pk_mul_f32 v[182:183], v[4:5], s[74:75] op_sel_hi:[1,0]
	v_pk_mul_f32 v[184:185], v[6:7], s[74:75] op_sel_hi:[1,0]
	v_pk_mul_f32 v[186:187], v[8:9], s[74:75] op_sel_hi:[1,0]
	v_exp_f32_e32 v180, v180
	v_exp_f32_e32 v181, v181
	v_exp_f32_e32 v182, v182
	v_exp_f32_e32 v183, v183
	v_exp_f32_e32 v184, v184
	v_exp_f32_e32 v185, v185
	v_exp_f32_e32 v186, v186
	v_exp_f32_e32 v187, v187
	v_pk_fma_f32 v[188:189], v[74:75], s[24:25], v[236:237] op_sel_hi:[1,0,0]
	v_pk_fma_f32 v[190:191], v[76:77], s[24:25], v[236:237] op_sel_hi:[1,0,0]
	v_pk_fma_f32 v[192:193], v[70:71], s[24:25], v[236:237] op_sel_hi:[1,0,0]
	v_pk_fma_f32 v[194:195], v[72:73], s[24:25], v[236:237] op_sel_hi:[1,0,0]
	v_pk_add_f32 v[180:181], v[180:181], 1.0 op_sel_hi:[1,0]
	v_pk_add_f32 v[182:183], v[182:183], 1.0 op_sel_hi:[1,0]
	v_pk_add_f32 v[184:185], v[184:185], 1.0 op_sel_hi:[1,0]
	v_pk_add_f32 v[186:187], v[186:187], 1.0 op_sel_hi:[1,0]
	v_rcp_f32_e32 v180, v180
	v_rcp_f32_e32 v181, v181
	v_rcp_f32_e32 v182, v182
	v_rcp_f32_e32 v183, v183
	v_rcp_f32_e32 v184, v184
	v_rcp_f32_e32 v185, v185
	v_rcp_f32_e32 v186, v186
	v_rcp_f32_e32 v187, v187
	v_pk_fma_f32 v[188:189], v[74:75], v[188:189], s[22:23] op_sel_hi:[1,1,0]
	v_pk_fma_f32 v[190:191], v[76:77], v[190:191], s[22:23] op_sel_hi:[1,1,0]
	v_pk_fma_f32 v[192:193], v[70:71], v[192:193], s[22:23] op_sel_hi:[1,1,0]
	v_pk_fma_f32 v[194:195], v[72:73], v[194:195], s[22:23] op_sel_hi:[1,1,0]
	v_pk_fma_f32 v[188:189], v[74:75], v[188:189], -2.0 op_sel_hi:[1,1,0]
	v_pk_fma_f32 v[190:191], v[76:77], v[190:191], -2.0 op_sel_hi:[1,1,0]
	v_pk_fma_f32 v[192:193], v[70:71], v[192:193], -2.0 op_sel_hi:[1,1,0]
	v_pk_fma_f32 v[194:195], v[72:73], v[194:195], -2.0 op_sel_hi:[1,1,0]
	v_pk_fma_f32 v[188:189], v[74:75], v[188:189], -2.0 op_sel_hi:[1,1,0]
	v_pk_fma_f32 v[190:191], v[76:77], v[190:191], -2.0 op_sel_hi:[1,1,0]
	v_pk_fma_f32 v[192:193], v[70:71], v[192:193], -2.0 op_sel_hi:[1,1,0]
	v_pk_fma_f32 v[194:195], v[72:73], v[194:195], -2.0 op_sel_hi:[1,1,0]
	v_pk_mul_f32 v[188:189], v[74:75], v[188:189]
	v_pk_mul_f32 v[190:191], v[76:77], v[190:191]
	v_pk_mul_f32 v[192:193], v[70:71], v[192:193]
	v_pk_mul_f32 v[194:195], v[72:73], v[194:195]
	v_pk_mul_f32 v[228:229], v[74:75], s[74:75] op_sel_hi:[1,0] neg_lo:[0,1] neg_hi:[0,1]
	v_pk_mul_f32 v[230:231], v[76:77], s[74:75] op_sel_hi:[1,0] neg_lo:[0,1] neg_hi:[0,1]
	v_pk_mul_f32 v[232:233], v[70:71], s[74:75] op_sel_hi:[1,0] neg_lo:[0,1] neg_hi:[0,1]
	v_pk_mul_f32 v[234:235], v[72:73], s[74:75] op_sel_hi:[1,0] neg_lo:[0,1] neg_hi:[0,1]
	v_sqrt_f32_e32 v188, v188
	v_sqrt_f32_e32 v189, v189
	v_sqrt_f32_e32 v190, v190
	v_sqrt_f32_e32 v191, v191
	v_sqrt_f32_e32 v192, v192
	v_sqrt_f32_e32 v193, v193
	v_sqrt_f32_e32 v194, v194
	v_sqrt_f32_e32 v195, v195
	v_exp_f32_e32 v228, v228
	v_exp_f32_e32 v229, v229
	v_exp_f32_e32 v230, v230
	v_exp_f32_e32 v231, v231
	v_exp_f32_e32 v232, v232
	v_exp_f32_e32 v233, v233
	v_exp_f32_e32 v234, v234
	v_exp_f32_e32 v235, v235
	s_waitcnt vmcnt(19)
; __device__ __forceinline__ unsigned cvt_pk_bf16(float lo, float hi) { unsigned r; asm volatile("v_cvt_pk_bf16_f32 %0, %1, %2" : "=v"(r) : "v"(lo), "v"(hi)); return r; }
;     __device__ __forceinline__ void operator()(AccMut acc, const Unit& u, int sw) const {
;     ...
;                 for (int n = 0; n < 2; ++n)
; #pragma unroll
;                     for (int jp = 0; jp < 2; ++jp) {
;                         const f32x2 z = (f32x2){acc[ai][1][m][n][2 * jp], acc[ai][1][m][n][2 * jp + 1]} * (-1.44269504f);
;                         f32x2 e; e.x = __builtin_amdgcn_exp2f(z.x); e.y = __builtin_amdgcn_exp2f(z.y); e = e + 1.0f;
;                         f32x2 ig; ig.x = __builtin_amdgcn_rcpf(e.x); ig.y = __builtin_amdgcn_rcpf(e.y);
;                         const f32x2 x2 = (f32x2){acc[ai][0][m][n][2 * jp], acc[ai][0][m][n][2 * jp + 1]} * 2.0f;
;                         f32x2 ser = x2 * (1.0f / 120.0f) + (1.0f / 24.0f); ser = ser * x2 + (1.0f / 6.0f); ser = ser * x2 + 0.5f; ser = ser * x2 + 1.0f; ser = ser * (-x2);
;                         f32x2 em = ser;
;                         if (__builtin_expect(__builtin_amdgcn_ballot_w64(x2.x <= -0.25f || x2.y <= -0.25f) != 0ull, 0)) {
;                             em.x = (x2.x > -0.25f) ? ser.x : (1.0f - fexp(x2.x)); em.y = (x2.y > -0.25f) ? ser.y : (1.0f - fexp(x2.y)); }
;                         const unsigned wv = xw[2 * n + jp];
;                         f32x2 sq; sq.x = __builtin_amdgcn_sqrtf(em.x); sq.y = __builtin_amdgcn_sqrtf(em.y);
;                         const f32x2 b2 = sq * ig * (f32x2){bf_lo(wv), bf_hi(wv)};
;                         bt[4 * n + 2 * jp] = b2.x; bt[4 * n + 2 * jp + 1] = b2.y; }
;                 u32x4 w; w.x = cvt_pk_bf16(bt[0], bt[1]); w.y = cvt_pk_bf16(bt[2], bt[3]); w.z = cvt_pk_bf16(bt[4], bt[5]); w.w = cvt_pk_bf16(bt[6], bt[7]);
;                 *(u32x4*)(BT + off) = w; }
; __device__ __forceinline__ void scan1_phase(const bf16_t* LA, const bf16_t* BT, int sw, View vw) {
;     ...
;             for (int i = 0; i < 8; ++i) {
;                 const float l0 = bf_lo(lw[i].x), l1 = bf_hi(lw[i].x), l2 = bf_lo(lw[i].y), l3 = bf_hi(lw[i].y);
;                 S[0] += l0; S[1] += l1; S[2] += l2; S[3] += l3;
;                 Hc[0] = fexp(l0) * Hc[0] + bf_lo(bw[i].x); Hc[1] = fexp(l1) * Hc[1] + bf_hi(bw[i].x); Hc[2] = fexp(l2) * Hc[2] + bf_lo(bw[i].y); Hc[3] = fexp(l3) * Hc[3] + bf_hi(bw[i].y); }
	v_lshlrev_b32_e32 v196, 16, v164
	v_and_b32_e32 v197, 0xffff0000, v164
	v_lshlrev_b32_e32 v198, 16, v165
	v_and_b32_e32 v199, 0xffff0000, v165
	v_lshlrev_b32_e32 v200, 16, v166
	v_and_b32_e32 v201, 0xffff0000, v166
	v_lshlrev_b32_e32 v202, 16, v167
	v_and_b32_e32 v203, 0xffff0000, v167
	v_pk_mul_f32 v[188:189], v[188:189], v[180:181]
	v_pk_mul_f32 v[190:191], v[190:191], v[182:183]
	v_pk_mul_f32 v[192:193], v[192:193], v[184:185]
	v_pk_mul_f32 v[194:195], v[194:195], v[186:187]
	v_pk_mul_f32 v[188:189], v[188:189], v[196:197]
	v_pk_mul_f32 v[190:191], v[190:191], v[198:199]
	v_pk_mul_f32 v[192:193], v[192:193], v[200:201]
	v_pk_mul_f32 v[194:195], v[194:195], v[202:203]
	v_cvt_pk_bf16_f32 v212, v188, v189
	v_cvt_pk_bf16_f32 v213, v190, v191
	v_cvt_pk_bf16_f32 v214, v192, v193
	v_cvt_pk_bf16_f32 v215, v194, v195
	global_store_dwordx4 v179, v[212:215], s[10:11] nt
	v_pk_fma_f32 v[216:217], v[228:229], v[216:217], v[188:189]
	v_pk_fma_f32 v[218:219], v[230:231], v[218:219], v[190:191]
	v_pk_fma_f32 v[240:241], v[232:233], v[240:241], v[192:193]
	v_pk_fma_f32 v[242:243], v[234:235], v[242:243], v[194:195]
	v_pk_mul_f32 v[26:27], v[26:27], v[228:229]
	v_pk_mul_f32 v[28:29], v[28:29], v[230:231]
	v_pk_mul_f32 v[30:31], v[30:31], v[232:233]
	v_pk_mul_f32 v[32:33], v[32:33], v[234:235]
	v_pk_add_f32 v[110:111], v[110:111], v[74:75]
	v_pk_add_f32 v[112:113], v[112:113], v[76:77]
	v_pk_add_f32 v[102:103], v[102:103], v[70:71]
	v_pk_add_f32 v[104:105], v[104:105], v[72:73]
	v_fmac_f32_dpp v216, v216, v26 row_shr:1 row_mask:0xf bank_mask:0xf
	v_fmac_f32_dpp v217, v217, v27 row_shr:1 row_mask:0xf bank_mask:0xf
	v_fmac_f32_dpp v218, v218, v28 row_shr:1 row_mask:0xf bank_mask:0xf
	v_fmac_f32_dpp v219, v219, v29 row_shr:1 row_mask:0xf bank_mask:0xf
	v_fmac_f32_dpp v240, v240, v30 row_shr:1 row_mask:0xf bank_mask:0xf
	v_fmac_f32_dpp v241, v241, v31 row_shr:1 row_mask:0xf bank_mask:0xf
	v_fmac_f32_dpp v242, v242, v32 row_shr:1 row_mask:0xf bank_mask:0xf
	v_fmac_f32_dpp v243, v243, v33 row_shr:1 row_mask:0xf bank_mask:0xf
	v_mul_f32_dpp v26, v26, v26 row_shr:1 row_mask:0xf bank_mask:0xf
	v_mul_f32_dpp v27, v27, v27 row_shr:1 row_mask:0xf bank_mask:0xf
	v_mul_f32_dpp v28, v28, v28 row_shr:1 row_mask:0xf bank_mask:0xf
	v_mul_f32_dpp v29, v29, v29 row_shr:1 row_mask:0xf bank_mask:0xf
	v_mul_f32_dpp v30, v30, v30 row_shr:1 row_mask:0xf bank_mask:0xf
	v_mul_f32_dpp v31, v31, v31 row_shr:1 row_mask:0xf bank_mask:0xf
	v_mul_f32_dpp v32, v32, v32 row_shr:1 row_mask:0xf bank_mask:0xf
	v_mul_f32_dpp v33, v33, v33 row_shr:1 row_mask:0xf bank_mask:0xf
	v_add_f32_dpp v110, v110, v110 row_shr:1 row_mask:0xf bank_mask:0xf
	v_add_f32_dpp v111, v111, v111 row_shr:1 row_mask:0xf bank_mask:0xf
	v_add_f32_dpp v112, v112, v112 row_shr:1 row_mask:0xf bank_mask:0xf
	v_add_f32_dpp v113, v113, v113 row_shr:1 row_mask:0xf bank_mask:0xf
	v_add_f32_dpp v102, v102, v102 row_shr:1 row_mask:0xf bank_mask:0xf
	v_add_f32_dpp v103, v103, v103 row_shr:1 row_mask:0xf bank_mask:0xf
	v_add_f32_dpp v104, v104, v104 row_shr:1 row_mask:0xf bank_mask:0xf
	v_add_f32_dpp v105, v105, v105 row_shr:1 row_mask:0xf bank_mask:0xf
	v_fmac_f32_dpp v216, v216, v26 row_shr:2 row_mask:0xf bank_mask:0xf
	v_fmac_f32_dpp v217, v217, v27 row_shr:2 row_mask:0xf bank_mask:0xf
	v_fmac_f32_dpp v218, v218, v28 row_shr:2 row_mask:0xf bank_mask:0xf
	v_fmac_f32_dpp v219, v219, v29 row_shr:2 row_mask:0xf bank_mask:0xf
	v_fmac_f32_dpp v240, v240, v30 row_shr:2 row_mask:0xf bank_mask:0xf
	v_fmac_f32_dpp v241, v241, v31 row_shr:2 row_mask:0xf bank_mask:0xf
	v_fmac_f32_dpp v242, v242, v32 row_shr:2 row_mask:0xf bank_mask:0xf
	v_fmac_f32_dpp v243, v243, v33 row_shr:2 row_mask:0xf bank_mask:0xf
	v_mul_f32_dpp v26, v26, v26 row_shr:2 row_mask:0xf bank_mask:0xf
	v_mul_f32_dpp v27, v27, v27 row_shr:2 row_mask:0xf bank_mask:0xf
	v_mul_f32_dpp v28, v28, v28 row_shr:2 row_mask:0xf bank_mask:0xf
	v_mul_f32_dpp v29, v29, v29 row_shr:2 row_mask:0xf bank_mask:0xf
	v_mul_f32_dpp v30, v30, v30 row_shr:2 row_mask:0xf bank_mask:0xf
; __device__ __forceinline__ float bf_lo(unsigned w) { return __uint_as_float(w << 16); }
; __device__ __forceinline__ float bf_hi(unsigned w) { return __uint_as_float(w & 0xffff0000u); }
; __device__ __forceinline__ float fexp(float x) { return __builtin_amdgcn_exp2f(1.44269504f * x); }
; __device__ __forceinline__ void scan1_phase(const bf16_t* LA, const bf16_t* BT, int sw, View vw) {
;     ...
;             for (int i = 0; i < 8; ++i) {
;                 const float l0 = bf_lo(lw[i].x), l1 = bf_hi(lw[i].x), l2 = bf_lo(lw[i].y), l3 = bf_hi(lw[i].y);
;                 S[0] += l0; S[1] += l1; S[2] += l2; S[3] += l3;
;                 Hc[0] = fexp(l0) * Hc[0] + bf_lo(bw[i].x); Hc[1] = fexp(l1) * Hc[1] + bf_hi(bw[i].x); Hc[2] = fexp(l2) * Hc[2] + bf_lo(bw[i].y); Hc[3] = fexp(l3) * Hc[3] + bf_hi(bw[i].y); }
;         }
;         *(f32x4*)(CP + (size_t)bq * E + 4 * quad) = (f32x4){S[0], S[1], S[2], S[3]};
;         *(f32x4*)(CH + (size_t)bq * E + 4 * quad) = (f32x4){Hc[0], Hc[1], Hc[2], Hc[3]};
	v_mul_f32_dpp v31, v31, v31 row_shr:2 row_mask:0xf bank_mask:0xf
	v_mul_f32_dpp v32, v32, v32 row_shr:2 row_mask:0xf bank_mask:0xf
	v_mul_f32_dpp v33, v33, v33 row_shr:2 row_mask:0xf bank_mask:0xf
	v_add_f32_dpp v110, v110, v110 row_shr:2 row_mask:0xf bank_mask:0xf
	v_add_f32_dpp v111, v111, v111 row_shr:2 row_mask:0xf bank_mask:0xf
	v_add_f32_dpp v112, v112, v112 row_shr:2 row_mask:0xf bank_mask:0xf
	v_add_f32_dpp v113, v113, v113 row_shr:2 row_mask:0xf bank_mask:0xf
	v_add_f32_dpp v102, v102, v102 row_shr:2 row_mask:0xf bank_mask:0xf
	v_add_f32_dpp v103, v103, v103 row_shr:2 row_mask:0xf bank_mask:0xf
	v_add_f32_dpp v104, v104, v104 row_shr:2 row_mask:0xf bank_mask:0xf
	v_add_f32_dpp v105, v105, v105 row_shr:2 row_mask:0xf bank_mask:0xf
	v_fmac_f32_dpp v216, v216, v26 row_shr:4 row_mask:0xf bank_mask:0xf
	v_fmac_f32_dpp v217, v217, v27 row_shr:4 row_mask:0xf bank_mask:0xf
	v_fmac_f32_dpp v218, v218, v28 row_shr:4 row_mask:0xf bank_mask:0xf
	v_fmac_f32_dpp v219, v219, v29 row_shr:4 row_mask:0xf bank_mask:0xf
	v_fmac_f32_dpp v240, v240, v30 row_shr:4 row_mask:0xf bank_mask:0xf
	v_fmac_f32_dpp v241, v241, v31 row_shr:4 row_mask:0xf bank_mask:0xf
	v_fmac_f32_dpp v242, v242, v32 row_shr:4 row_mask:0xf bank_mask:0xf
	v_fmac_f32_dpp v243, v243, v33 row_shr:4 row_mask:0xf bank_mask:0xf
	v_mul_f32_dpp v26, v26, v26 row_shr:4 row_mask:0xf bank_mask:0xf
	v_mul_f32_dpp v27, v27, v27 row_shr:4 row_mask:0xf bank_mask:0xf
	v_mul_f32_dpp v28, v28, v28 row_shr:4 row_mask:0xf bank_mask:0xf
	v_mul_f32_dpp v29, v29, v29 row_shr:4 row_mask:0xf bank_mask:0xf
	v_mul_f32_dpp v30, v30, v30 row_shr:4 row_mask:0xf bank_mask:0xf
	v_mul_f32_dpp v31, v31, v31 row_shr:4 row_mask:0xf bank_mask:0xf
	v_mul_f32_dpp v32, v32, v32 row_shr:4 row_mask:0xf bank_mask:0xf
	v_mul_f32_dpp v33, v33, v33 row_shr:4 row_mask:0xf bank_mask:0xf
	v_add_f32_dpp v110, v110, v110 row_shr:4 row_mask:0xf bank_mask:0xf
	v_add_f32_dpp v111, v111, v111 row_shr:4 row_mask:0xf bank_mask:0xf
	v_add_f32_dpp v112, v112, v112 row_shr:4 row_mask:0xf bank_mask:0xf
	v_add_f32_dpp v113, v113, v113 row_shr:4 row_mask:0xf bank_mask:0xf
	v_add_f32_dpp v102, v102, v102 row_shr:4 row_mask:0xf bank_mask:0xf
	v_add_f32_dpp v103, v103, v103 row_shr:4 row_mask:0xf bank_mask:0xf
	v_add_f32_dpp v104, v104, v104 row_shr:4 row_mask:0xf bank_mask:0xf
	v_add_f32_dpp v105, v105, v105 row_shr:4 row_mask:0xf bank_mask:0xf
	v_fmac_f32_dpp v216, v216, v26 row_shr:8 row_mask:0xf bank_mask:0xf
	v_fmac_f32_dpp v217, v217, v27 row_shr:8 row_mask:0xf bank_mask:0xf
	v_fmac_f32_dpp v218, v218, v28 row_shr:8 row_mask:0xf bank_mask:0xf
	v_fmac_f32_dpp v219, v219, v29 row_shr:8 row_mask:0xf bank_mask:0xf
	v_fmac_f32_dpp v240, v240, v30 row_shr:8 row_mask:0xf bank_mask:0xf
	v_fmac_f32_dpp v241, v241, v31 row_shr:8 row_mask:0xf bank_mask:0xf
	v_fmac_f32_dpp v242, v242, v32 row_shr:8 row_mask:0xf bank_mask:0xf
	v_fmac_f32_dpp v243, v243, v33 row_shr:8 row_mask:0xf bank_mask:0xf
	v_add_f32_dpp v110, v110, v110 row_shr:8 row_mask:0xf bank_mask:0xf
	v_add_f32_dpp v111, v111, v111 row_shr:8 row_mask:0xf bank_mask:0xf
	v_add_f32_dpp v112, v112, v112 row_shr:8 row_mask:0xf bank_mask:0xf
	v_add_f32_dpp v113, v113, v113 row_shr:8 row_mask:0xf bank_mask:0xf
	v_add_f32_dpp v102, v102, v102 row_shr:8 row_mask:0xf bank_mask:0xf
	v_add_f32_dpp v103, v103, v103 row_shr:8 row_mask:0xf bank_mask:0xf
	v_add_f32_dpp v104, v104, v104 row_shr:8 row_mask:0xf bank_mask:0xf
	v_add_f32_dpp v105, v105, v105 row_shr:8 row_mask:0xf bank_mask:0xf
	v_mbcnt_lo_u32_b32 v180, -1, 0
	v_mbcnt_hi_u32_b32 v180, -1, v180
	v_and_b32_e32 v180, 15, v180
	v_cmp_eq_u32_e32 vcc, 15, v180
	v_add_u32_e32 v181, 0x4000, v239
	v_add_u32_e32 v182, 0x404000, v239
	s_mov_b64 exec, vcc
	global_store_dwordx4 v181, v[110:113], s[26:27]
	global_store_dwordx4 v181, v[102:105], s[26:27] offset:16
	global_store_dwordx4 v182, v[216:219], s[26:27]
	global_store_dwordx4 v182, v[240:243], s[26:27] offset:16
	s_mov_b64 exec, -1
